# P1 epilogue: the 64 global_store_dwordx4 of the tile outputs marked nt (streaming) so they do not displace the operand tiles the XCD's workgroups share in L2
# speedup vs baseline: 1.0090x; 1.0090x over previous
; __device__ __forceinline__ unsigned pk2(float lo, float hi) { f32x2_t v = {lo, hi}; bf16x2_t b = __builtin_convertvector(v, bf16x2_t); return __builtin_bit_cast(unsigned, b); }
; __device__ __forceinline__ float fsigmoid(float x) { return __builtin_amdgcn_rcpf(1.f + fexp(-x)); }
;     ...
;         for (int tt = 0; tt < 4; ++tt) {
;           u16* srow = stg + (tt * 32 + l31) * LD;
; #pragma unroll
;           for (int ct = 0; ct < 2; ++ct)
; #pragma unroll
;             for (int rq = 0; rq < 4; ++rq) {
;               float v[4];
; #pragma unroll
;               for (int e = 0; e < 4; ++e) { v[e] = acc[ct][tt][rq * 4 + e] * rsv[tt]; if (act) v[e] = v[e] * fsigmoid(v[e]); }
;               u32x2 w; w.x = pk2(v[0], v[1]); w.y = pk2(v[2], v[3]);
;               *(u32x2*)(srow + ct * 32 + 8 * rq + 4 * h) = w;
.LBB0_145:
	s_andn2_b64 vcc, exec, s[36:37]
	s_cbranch_vccnz .Lp1_raw
	s_waitcnt vmcnt(3)
	v_mul_f32_e32 v7, v114, v10
	v_mul_f32_e32 v9, 0xbfb8aa3b, v7
	v_mul_f32_e32 v11, v115, v10
	v_exp_f32_e32 v9, v9
	v_mul_f32_e32 v13, 0xbfb8aa3b, v11
	v_exp_f32_e32 v13, v13
	v_mul_f32_e32 v14, v116, v10
	v_add_f32_e32 v9, 1.0, v9
	v_rcp_f32_e32 v9, v9
	v_add_f32_e32 v13, 1.0, v13
	v_mul_f32_e32 v15, 0xbfb8aa3b, v14
	v_rcp_f32_e32 v13, v13
	v_exp_f32_e32 v15, v15
	v_mul_f32_e32 v9, v7, v9
	v_cndmask_b32_e64 v7, v7, v9, s[36:37]
	v_mul_f32_e32 v9, v11, v13
	v_add_f32_e32 v13, 1.0, v15
	v_mul_f32_e32 v15, v117, v10
	v_mul_f32_e32 v16, 0xbfb8aa3b, v15
	v_rcp_f32_e32 v13, v13
	v_exp_f32_e32 v16, v16
	v_cndmask_b32_e64 v9, v11, v9, s[36:37]
	v_mul_u32_u24_e32 v2, 0x90, v225
	v_mul_f32_e32 v11, v14, v13
	v_add_f32_e32 v13, 1.0, v16
	v_mul_f32_e32 v16, v118, v10
	v_cndmask_b32_e64 v11, v14, v11, s[36:37]
	v_mul_f32_e32 v14, 0xbfb8aa3b, v16
	v_rcp_f32_e32 v13, v13
	v_exp_f32_e32 v17, v14
	v_cvt_pk_bf16_f32 v14, v7, v9
	v_mul_f32_e32 v9, v119, v10
	v_mul_f32_e32 v13, v15, v13
	v_add_f32_e32 v7, 1.0, v17
	v_cndmask_b32_e64 v13, v15, v13, s[36:37]
	v_rcp_f32_e32 v7, v7
	v_mul_f32_e32 v15, 0xbfb8aa3b, v9
	v_exp_f32_e32 v17, v15
	v_cvt_pk_bf16_f32 v15, v11, v13
	v_mul_f32_e32 v7, v16, v7
	v_mul_f32_e32 v13, v120, v10
	v_cndmask_b32_e64 v7, v16, v7, s[36:37]
	v_add_f32_e32 v11, 1.0, v17
	v_mul_f32_e32 v16, 0xbfb8aa3b, v13
	v_mul_f32_e32 v17, v121, v10
	v_exp_f32_e32 v16, v16
	v_mul_f32_e32 v146, 0xbfb8aa3b, v17
	v_exp_f32_e32 v146, v146
	v_rcp_f32_e32 v11, v11
	v_add_f32_e32 v16, 1.0, v16
	v_rcp_f32_e32 v16, v16
	v_add_f32_e32 v146, 1.0, v146
	v_rcp_f32_e32 v146, v146
	v_mul_f32_e32 v11, v9, v11
	v_cndmask_b32_e64 v9, v9, v11, s[36:37]
	v_mul_f32_e32 v11, v13, v16
	v_cndmask_b32_e64 v11, v13, v11, s[36:37]
	v_mul_f32_e32 v13, v17, v146
	v_cndmask_b32_e64 v13, v17, v13, s[36:37]
	v_cvt_pk_bf16_f32 v16, v7, v9
	v_mul_f32_e32 v7, v122, v10
	v_cvt_pk_bf16_f32 v17, v11, v13
	v_mul_f32_e32 v9, 0xbfb8aa3b, v7
	v_mul_f32_e32 v11, v123, v10
	v_exp_f32_e32 v9, v9
	v_mul_f32_e32 v13, 0xbfb8aa3b, v11
	v_exp_f32_e32 v13, v13
	v_add3_u32 v2, s7, v5, v2
	ds_write2_b64 v2, v[14:15], v[16:17] offset1:2
	v_add_f32_e32 v9, 1.0, v9
	v_mul_f32_e32 v14, v124, v10
	v_rcp_f32_e32 v9, v9
	v_add_f32_e32 v13, 1.0, v13
	v_mul_f32_e32 v15, 0xbfb8aa3b, v14
	v_rcp_f32_e32 v13, v13
	v_exp_f32_e32 v15, v15
	v_mul_f32_e32 v9, v7, v9
	v_cndmask_b32_e64 v7, v7, v9, s[36:37]
	v_mul_f32_e32 v9, v11, v13
	v_add_f32_e32 v13, 1.0, v15
	v_mul_f32_e32 v15, v125, v10
	v_mul_f32_e32 v16, 0xbfb8aa3b, v15
	v_rcp_f32_e32 v13, v13
	v_exp_f32_e32 v16, v16
	v_cndmask_b32_e64 v9, v11, v9, s[36:37]
	s_add_u32 s38, s0, s38
	v_mul_f32_e32 v11, v14, v13
	v_add_f32_e32 v13, 1.0, v16
	v_mul_f32_e32 v16, v126, v10
	v_cndmask_b32_e64 v11, v14, v11, s[36:37]
	v_mul_f32_e32 v14, 0xbfb8aa3b, v16
	v_rcp_f32_e32 v13, v13
	v_exp_f32_e32 v17, v14
	v_cvt_pk_bf16_f32 v14, v7, v9
	v_mul_f32_e32 v9, v127, v10
	v_mul_f32_e32 v13, v15, v13
	v_add_f32_e32 v7, 1.0, v17
	v_cndmask_b32_e64 v13, v15, v13, s[36:37]
	v_rcp_f32_e32 v7, v7
	v_mul_f32_e32 v15, 0xbfb8aa3b, v9
	v_exp_f32_e32 v17, v15
	v_cvt_pk_bf16_f32 v15, v11, v13
	v_mul_f32_e32 v7, v16, v7
	v_mul_f32_e32 v13, v128, v10
	v_cndmask_b32_e64 v7, v16, v7, s[36:37]
	v_add_f32_e32 v11, 1.0, v17
	v_mul_f32_e32 v16, 0xbfb8aa3b, v13
	v_mul_f32_e32 v17, v129, v10
	v_exp_f32_e32 v16, v16
	v_mul_f32_e32 v146, 0xbfb8aa3b, v17
	v_exp_f32_e32 v146, v146
	v_rcp_f32_e32 v11, v11
	v_add_f32_e32 v16, 1.0, v16
	v_rcp_f32_e32 v16, v16
	v_add_f32_e32 v146, 1.0, v146
	v_rcp_f32_e32 v146, v146
	v_mul_f32_e32 v11, v9, v11
	v_cndmask_b32_e64 v9, v9, v11, s[36:37]
	v_mul_f32_e32 v11, v13, v16
	v_cndmask_b32_e64 v11, v13, v11, s[36:37]
	v_mul_f32_e32 v13, v17, v146
	v_cndmask_b32_e64 v13, v17, v13, s[36:37]
	v_cvt_pk_bf16_f32 v16, v7, v9
	v_mul_f32_e32 v7, v130, v10
	v_cvt_pk_bf16_f32 v17, v11, v13
	v_mul_f32_e32 v9, 0xbfb8aa3b, v7
	v_mul_f32_e32 v11, v131, v10
	v_exp_f32_e32 v9, v9
	v_mul_f32_e32 v13, 0xbfb8aa3b, v11
	v_exp_f32_e32 v13, v13
	ds_write2_b64 v2, v[14:15], v[16:17] offset0:4 offset1:6
	v_add_f32_e32 v9, 1.0, v9
	v_mul_f32_e32 v14, v132, v10
	v_rcp_f32_e32 v9, v9
	v_add_f32_e32 v13, 1.0, v13
	v_mul_f32_e32 v15, 0xbfb8aa3b, v14
	v_rcp_f32_e32 v13, v13
	v_exp_f32_e32 v15, v15
	v_mul_f32_e32 v9, v7, v9
	v_cndmask_b32_e64 v7, v7, v9, s[36:37]
	v_mul_f32_e32 v9, v11, v13
	v_add_f32_e32 v13, 1.0, v15
	v_mul_f32_e32 v15, v133, v10
	v_mul_f32_e32 v16, 0xbfb8aa3b, v15
	v_rcp_f32_e32 v13, v13
	v_exp_f32_e32 v16, v16
	v_cndmask_b32_e64 v9, v11, v9, s[36:37]
	s_addc_u32 s39, s1, s39
	v_mul_f32_e32 v11, v14, v13
	v_add_f32_e32 v13, 1.0, v16
	v_mul_f32_e32 v16, v134, v10
	v_cndmask_b32_e64 v11, v14, v11, s[36:37]
	v_mul_f32_e32 v14, 0xbfb8aa3b, v16
	v_rcp_f32_e32 v13, v13
	v_exp_f32_e32 v17, v14
	v_cvt_pk_bf16_f32 v14, v7, v9
	v_mul_f32_e32 v9, v135, v10
	v_mul_f32_e32 v13, v15, v13
	v_add_f32_e32 v7, 1.0, v17
	v_cndmask_b32_e64 v13, v15, v13, s[36:37]
	v_rcp_f32_e32 v7, v7
	v_mul_f32_e32 v15, 0xbfb8aa3b, v9
	v_exp_f32_e32 v17, v15
	v_cvt_pk_bf16_f32 v15, v11, v13
	v_mul_f32_e32 v7, v16, v7
	v_mul_f32_e32 v13, v136, v10
	v_cndmask_b32_e64 v7, v16, v7, s[36:37]
	v_add_f32_e32 v11, 1.0, v17
	v_mul_f32_e32 v16, 0xbfb8aa3b, v13
	v_mul_f32_e32 v17, v137, v10
	v_exp_f32_e32 v16, v16
	v_mul_f32_e32 v146, 0xbfb8aa3b, v17
	v_exp_f32_e32 v146, v146
	v_rcp_f32_e32 v11, v11
	v_add_f32_e32 v16, 1.0, v16
	v_rcp_f32_e32 v16, v16
	v_add_f32_e32 v146, 1.0, v146
	v_rcp_f32_e32 v146, v146
	v_mul_f32_e32 v11, v9, v11
	v_cndmask_b32_e64 v9, v9, v11, s[36:37]
	v_mul_f32_e32 v11, v13, v16
	v_cndmask_b32_e64 v11, v13, v11, s[36:37]
; __device__ __forceinline__ unsigned pk2(float lo, float hi) { f32x2_t v = {lo, hi}; bf16x2_t b = __builtin_convertvector(v, bf16x2_t); return __builtin_bit_cast(unsigned, b); }
; __device__ __forceinline__ float fsigmoid(float x) { return __builtin_amdgcn_rcpf(1.f + fexp(-x)); }
;     ...
;         for (int tt = 0; tt < 4; ++tt) {
;           u16* srow = stg + (tt * 32 + l31) * LD;
; #pragma unroll
;           for (int ct = 0; ct < 2; ++ct)
; #pragma unroll
;             for (int rq = 0; rq < 4; ++rq) {
;               float v[4];
; #pragma unroll
;               for (int e = 0; e < 4; ++e) { v[e] = acc[ct][tt][rq * 4 + e] * rsv[tt]; if (act) v[e] = v[e] * fsigmoid(v[e]); }
;               u32x2 w; w.x = pk2(v[0], v[1]); w.y = pk2(v[2], v[3]);
;               *(u32x2*)(srow + ct * 32 + 8 * rq + 4 * h) = w;
	v_mul_f32_e32 v13, v17, v146
	v_cndmask_b32_e64 v13, v17, v13, s[36:37]
	v_cvt_pk_bf16_f32 v16, v7, v9
	v_mul_f32_e32 v7, v138, v10
	v_cvt_pk_bf16_f32 v17, v11, v13
	v_mul_f32_e32 v9, 0xbfb8aa3b, v7
	v_mul_f32_e32 v11, v139, v10
	v_exp_f32_e32 v9, v9
	v_mul_f32_e32 v13, 0xbfb8aa3b, v11
	v_exp_f32_e32 v13, v13
	ds_write2_b64 v2, v[14:15], v[16:17] offset0:8 offset1:10
	v_add_f32_e32 v9, 1.0, v9
	v_mul_f32_e32 v14, v140, v10
	v_rcp_f32_e32 v9, v9
	v_add_f32_e32 v13, 1.0, v13
	v_mul_f32_e32 v15, 0xbfb8aa3b, v14
	v_rcp_f32_e32 v13, v13
	v_exp_f32_e32 v15, v15
	v_mul_f32_e32 v9, v7, v9
	v_cndmask_b32_e64 v7, v7, v9, s[36:37]
	v_mul_f32_e32 v9, v11, v13
	v_add_f32_e32 v13, 1.0, v15
	v_mul_f32_e32 v15, v141, v10
	v_mul_f32_e32 v16, 0xbfb8aa3b, v15
	v_rcp_f32_e32 v13, v13
	v_exp_f32_e32 v16, v16
	v_cndmask_b32_e64 v9, v11, v9, s[36:37]
	s_load_dwordx2 s[38:39], s[38:39], 0x0
	v_mul_f32_e32 v11, v14, v13
	v_add_f32_e32 v13, 1.0, v16
	v_mul_f32_e32 v16, v142, v10
	v_cndmask_b32_e64 v11, v14, v11, s[36:37]
	v_mul_f32_e32 v14, 0xbfb8aa3b, v16
	v_rcp_f32_e32 v13, v13
	v_exp_f32_e32 v17, v14
	v_cvt_pk_bf16_f32 v14, v7, v9
	v_mul_f32_e32 v9, v143, v10
	v_mul_f32_e32 v13, v15, v13
	v_add_f32_e32 v7, 1.0, v17
	v_cndmask_b32_e64 v13, v15, v13, s[36:37]
	v_rcp_f32_e32 v7, v7
	v_mul_f32_e32 v15, 0xbfb8aa3b, v9
	v_exp_f32_e32 v17, v15
	v_cvt_pk_bf16_f32 v15, v11, v13
	v_mul_f32_e32 v7, v16, v7
	v_mul_f32_e32 v13, v144, v10
	v_cndmask_b32_e64 v7, v16, v7, s[36:37]
	v_add_f32_e32 v11, 1.0, v17
	v_mul_f32_e32 v16, 0xbfb8aa3b, v13
	v_mul_f32_e32 v17, v145, v10
	v_exp_f32_e32 v16, v16
	v_mul_f32_e32 v146, 0xbfb8aa3b, v17
	v_exp_f32_e32 v146, v146
	v_rcp_f32_e32 v11, v11
	v_add_f32_e32 v16, 1.0, v16
	v_rcp_f32_e32 v16, v16
	v_add_f32_e32 v146, 1.0, v146
	v_rcp_f32_e32 v146, v146
	v_mul_f32_e32 v11, v9, v11
	v_cndmask_b32_e64 v9, v9, v11, s[36:37]
	v_mul_f32_e32 v11, v13, v16
	v_cndmask_b32_e64 v11, v13, v11, s[36:37]
	v_mul_f32_e32 v13, v17, v146
	v_cndmask_b32_e64 v13, v17, v13, s[36:37]
	v_cvt_pk_bf16_f32 v16, v7, v9
	s_waitcnt vmcnt(2)
	v_mul_f32_e32 v7, v82, v8
	v_cvt_pk_bf16_f32 v17, v11, v13
	v_mul_f32_e32 v9, 0xbfb8aa3b, v7
	v_mul_f32_e32 v11, v83, v8
	v_exp_f32_e32 v9, v9
	v_mul_f32_e32 v13, 0xbfb8aa3b, v11
	v_exp_f32_e32 v13, v13
	ds_write2_b64 v2, v[14:15], v[16:17] offset0:12 offset1:14
	v_add_f32_e32 v9, 1.0, v9
	v_mul_f32_e32 v14, v84, v8
	v_rcp_f32_e32 v9, v9
	v_add_f32_e32 v13, 1.0, v13
	v_mul_f32_e32 v15, 0xbfb8aa3b, v14
	v_rcp_f32_e32 v13, v13
	v_exp_f32_e32 v15, v15
	v_mul_f32_e32 v9, v7, v9
	v_cndmask_b32_e64 v7, v7, v9, s[36:37]
	v_mul_f32_e32 v9, v11, v13
	v_add_f32_e32 v13, 1.0, v15
	v_mul_f32_e32 v15, v85, v8
	v_mul_f32_e32 v16, 0xbfb8aa3b, v15
	v_rcp_f32_e32 v13, v13
	v_exp_f32_e32 v16, v16
	v_cndmask_b32_e64 v9, v11, v9, s[36:37]
	s_add_i32 s20, s35, s64
	v_mul_f32_e32 v11, v14, v13
	v_add_f32_e32 v13, 1.0, v16
	v_mul_f32_e32 v16, v86, v8
	v_cndmask_b32_e64 v11, v14, v11, s[36:37]
	v_mul_f32_e32 v14, 0xbfb8aa3b, v16
	v_rcp_f32_e32 v13, v13
	v_exp_f32_e32 v17, v14
	v_cvt_pk_bf16_f32 v14, v7, v9
	v_mul_f32_e32 v9, v87, v8
	v_mul_f32_e32 v13, v15, v13
	v_add_f32_e32 v7, 1.0, v17
	v_cndmask_b32_e64 v13, v15, v13, s[36:37]
	v_rcp_f32_e32 v7, v7
	v_mul_f32_e32 v15, 0xbfb8aa3b, v9
	v_exp_f32_e32 v17, v15
	v_cvt_pk_bf16_f32 v15, v11, v13
	v_mul_f32_e32 v7, v16, v7
	v_mul_f32_e32 v13, v88, v8
	v_cndmask_b32_e64 v7, v16, v7, s[36:37]
	v_add_f32_e32 v11, 1.0, v17
	v_mul_f32_e32 v16, 0xbfb8aa3b, v13
	v_mul_f32_e32 v17, v89, v8
	v_exp_f32_e32 v16, v16
	v_mul_f32_e32 v146, 0xbfb8aa3b, v17
	v_exp_f32_e32 v146, v146
	v_rcp_f32_e32 v11, v11
	v_add_f32_e32 v16, 1.0, v16
	v_rcp_f32_e32 v16, v16
	v_add_f32_e32 v146, 1.0, v146
	v_rcp_f32_e32 v146, v146
	v_mul_f32_e32 v11, v9, v11
	v_cndmask_b32_e64 v9, v9, v11, s[36:37]
	v_mul_f32_e32 v11, v13, v16
	v_cndmask_b32_e64 v11, v13, v11, s[36:37]
	v_mul_f32_e32 v13, v17, v146
	v_cndmask_b32_e64 v13, v17, v13, s[36:37]
	v_cvt_pk_bf16_f32 v16, v7, v9
	v_mul_f32_e32 v9, v90, v8
	v_cvt_pk_bf16_f32 v17, v11, v13
	v_mul_f32_e32 v11, 0xbfb8aa3b, v9
	v_mul_f32_e32 v13, v91, v8
	v_exp_f32_e32 v11, v11
	v_mul_f32_e32 v146, 0xbfb8aa3b, v13
	v_exp_f32_e32 v146, v146
	v_add_u32_e32 v7, 0x1000, v2
	ds_write2_b64 v7, v[14:15], v[16:17] offset0:64 offset1:66
	v_add_f32_e32 v11, 1.0, v11
	v_mul_f32_e32 v15, v92, v8
	v_rcp_f32_e32 v11, v11
	v_add_f32_e32 v14, 1.0, v146
	v_mul_f32_e32 v16, 0xbfb8aa3b, v15
	v_rcp_f32_e32 v14, v14
	v_exp_f32_e32 v16, v16
	v_mul_f32_e32 v11, v9, v11
	v_cndmask_b32_e64 v9, v9, v11, s[36:37]
	v_mul_f32_e32 v11, v13, v14
	v_add_f32_e32 v14, 1.0, v16
	v_mul_f32_e32 v16, v93, v8
	v_mul_f32_e32 v17, 0xbfb8aa3b, v16
	v_rcp_f32_e32 v14, v14
	v_exp_f32_e32 v17, v17
	v_cndmask_b32_e64 v11, v13, v11, s[36:37]
	v_mov_b32_e32 v153, v3
	v_mul_f32_e32 v13, v15, v14
	v_add_f32_e32 v14, 1.0, v17
	v_mul_f32_e32 v17, v94, v8
	v_cndmask_b32_e64 v13, v15, v13, s[36:37]
	v_rcp_f32_e32 v14, v14
	v_mul_f32_e32 v15, 0xbfb8aa3b, v17
	v_exp_f32_e32 v15, v15
	v_mul_f32_e32 v14, v16, v14
	v_cndmask_b32_e64 v16, v16, v14, s[36:37]
	v_cvt_pk_bf16_f32 v14, v9, v11
	v_add_f32_e32 v9, 1.0, v15
	v_mul_f32_e32 v11, v95, v8
	v_rcp_f32_e32 v9, v9
	v_mul_f32_e32 v15, 0xbfb8aa3b, v11
	v_exp_f32_e32 v146, v15
	v_cvt_pk_bf16_f32 v15, v13, v16
	v_mul_f32_e32 v9, v17, v9
	v_mul_f32_e32 v16, v96, v8
	v_cndmask_b32_e64 v9, v17, v9, s[36:37]
	v_add_f32_e32 v13, 1.0, v146
	v_mul_f32_e32 v17, 0xbfb8aa3b, v16
	v_mul_f32_e32 v146, v97, v8
	v_exp_f32_e32 v17, v17
	v_mul_f32_e32 v148, 0xbfb8aa3b, v146
	v_exp_f32_e32 v148, v148
	v_rcp_f32_e32 v13, v13
	v_add_f32_e32 v17, 1.0, v17
	v_rcp_f32_e32 v17, v17
	v_add_f32_e32 v148, 1.0, v148
	v_rcp_f32_e32 v148, v148
; __device__ __forceinline__ unsigned pk2(float lo, float hi) { f32x2_t v = {lo, hi}; bf16x2_t b = __builtin_convertvector(v, bf16x2_t); return __builtin_bit_cast(unsigned, b); }
; __device__ __forceinline__ float fsigmoid(float x) { return __builtin_amdgcn_rcpf(1.f + fexp(-x)); }
;     ...
;         for (int tt = 0; tt < 4; ++tt) {
;           u16* srow = stg + (tt * 32 + l31) * LD;
; #pragma unroll
;           for (int ct = 0; ct < 2; ++ct)
; #pragma unroll
;             for (int rq = 0; rq < 4; ++rq) {
;               float v[4];
; #pragma unroll
;               for (int e = 0; e < 4; ++e) { v[e] = acc[ct][tt][rq * 4 + e] * rsv[tt]; if (act) v[e] = v[e] * fsigmoid(v[e]); }
;               u32x2 w; w.x = pk2(v[0], v[1]); w.y = pk2(v[2], v[3]);
;               *(u32x2*)(srow + ct * 32 + 8 * rq + 4 * h) = w;
	v_mul_f32_e32 v13, v11, v13
	v_cndmask_b32_e64 v11, v11, v13, s[36:37]
	v_mul_f32_e32 v13, v16, v17
	v_cndmask_b32_e64 v13, v16, v13, s[36:37]
	v_mul_f32_e32 v16, v146, v148
	v_cndmask_b32_e64 v17, v146, v16, s[36:37]
	v_cvt_pk_bf16_f32 v16, v9, v11
	v_mul_f32_e32 v9, v98, v8
	v_cvt_pk_bf16_f32 v17, v13, v17
	v_mul_f32_e32 v11, 0xbfb8aa3b, v9
	v_mul_f32_e32 v13, v99, v8
	v_exp_f32_e32 v11, v11
	v_mul_f32_e32 v146, 0xbfb8aa3b, v13
	v_exp_f32_e32 v146, v146
	ds_write2_b64 v7, v[14:15], v[16:17] offset0:68 offset1:70
	v_add_f32_e32 v11, 1.0, v11
	v_mul_f32_e32 v15, v100, v8
	v_rcp_f32_e32 v11, v11
	v_add_f32_e32 v14, 1.0, v146
	v_mul_f32_e32 v16, 0xbfb8aa3b, v15
	v_rcp_f32_e32 v14, v14
	v_exp_f32_e32 v16, v16
	v_mul_f32_e32 v11, v9, v11
	v_cndmask_b32_e64 v9, v9, v11, s[36:37]
	v_mul_f32_e32 v11, v13, v14
	v_add_f32_e32 v14, 1.0, v16
	v_mul_f32_e32 v16, v101, v8
	v_mul_f32_e32 v17, 0xbfb8aa3b, v16
	v_rcp_f32_e32 v14, v14
	v_exp_f32_e32 v17, v17
	v_cndmask_b32_e64 v11, v13, v11, s[36:37]
	v_mul_f32_e32 v13, v15, v14
	v_add_f32_e32 v14, 1.0, v17
	v_mul_f32_e32 v17, v102, v8
	v_cndmask_b32_e64 v13, v15, v13, s[36:37]
	v_rcp_f32_e32 v14, v14
	v_mul_f32_e32 v15, 0xbfb8aa3b, v17
	v_exp_f32_e32 v15, v15
	v_mul_f32_e32 v14, v16, v14
	v_cndmask_b32_e64 v16, v16, v14, s[36:37]
	v_cvt_pk_bf16_f32 v14, v9, v11
	v_add_f32_e32 v9, 1.0, v15
	v_mul_f32_e32 v11, v103, v8
	v_rcp_f32_e32 v9, v9
	v_mul_f32_e32 v15, 0xbfb8aa3b, v11
	v_exp_f32_e32 v146, v15
	v_cvt_pk_bf16_f32 v15, v13, v16
	v_mul_f32_e32 v9, v17, v9
	v_mul_f32_e32 v16, v104, v8
	v_cndmask_b32_e64 v9, v17, v9, s[36:37]
	v_add_f32_e32 v13, 1.0, v146
	v_mul_f32_e32 v17, 0xbfb8aa3b, v16
	v_mul_f32_e32 v146, v105, v8
	v_exp_f32_e32 v17, v17
	v_mul_f32_e32 v148, 0xbfb8aa3b, v146
	v_exp_f32_e32 v148, v148
	v_rcp_f32_e32 v13, v13
	v_add_f32_e32 v17, 1.0, v17
	v_rcp_f32_e32 v17, v17
	v_add_f32_e32 v148, 1.0, v148
	v_rcp_f32_e32 v148, v148
	v_mul_f32_e32 v13, v11, v13
	v_cndmask_b32_e64 v11, v11, v13, s[36:37]
	v_mul_f32_e32 v13, v16, v17
	v_cndmask_b32_e64 v13, v16, v13, s[36:37]
	v_mul_f32_e32 v16, v146, v148
	v_cndmask_b32_e64 v17, v146, v16, s[36:37]
	v_cvt_pk_bf16_f32 v16, v9, v11
	v_mul_f32_e32 v9, v106, v8
	v_cvt_pk_bf16_f32 v17, v13, v17
	v_mul_f32_e32 v11, 0xbfb8aa3b, v9
	v_mul_f32_e32 v13, v107, v8
	v_exp_f32_e32 v11, v11
	v_mul_f32_e32 v146, 0xbfb8aa3b, v13
	v_exp_f32_e32 v146, v146
	ds_write2_b64 v7, v[14:15], v[16:17] offset0:72 offset1:74
	v_add_f32_e32 v11, 1.0, v11
	v_mul_f32_e32 v15, v108, v8
	v_rcp_f32_e32 v11, v11
	v_add_f32_e32 v14, 1.0, v146
	v_mul_f32_e32 v16, 0xbfb8aa3b, v15
	v_rcp_f32_e32 v14, v14
	v_exp_f32_e32 v16, v16
	v_mul_f32_e32 v11, v9, v11
	v_cndmask_b32_e64 v9, v9, v11, s[36:37]
	v_mul_f32_e32 v11, v13, v14
	v_add_f32_e32 v14, 1.0, v16
	v_mul_f32_e32 v16, v109, v8
	v_mul_f32_e32 v17, 0xbfb8aa3b, v16
	v_rcp_f32_e32 v14, v14
	v_exp_f32_e32 v17, v17
	v_cndmask_b32_e64 v11, v13, v11, s[36:37]
	v_mul_f32_e32 v13, v15, v14
	v_add_f32_e32 v14, 1.0, v17
	v_mul_f32_e32 v17, v110, v8
	v_cndmask_b32_e64 v13, v15, v13, s[36:37]
	v_rcp_f32_e32 v14, v14
	v_mul_f32_e32 v15, 0xbfb8aa3b, v17
	v_exp_f32_e32 v15, v15
	v_mul_f32_e32 v14, v16, v14
	v_cndmask_b32_e64 v16, v16, v14, s[36:37]
	v_cvt_pk_bf16_f32 v14, v9, v11
	v_add_f32_e32 v9, 1.0, v15
	v_mul_f32_e32 v11, v111, v8
	v_rcp_f32_e32 v9, v9
	v_mul_f32_e32 v15, 0xbfb8aa3b, v11
	v_exp_f32_e32 v146, v15
	v_cvt_pk_bf16_f32 v15, v13, v16
	v_mul_f32_e32 v9, v17, v9
	v_mul_f32_e32 v16, v112, v8
	v_cndmask_b32_e64 v9, v17, v9, s[36:37]
	v_add_f32_e32 v13, 1.0, v146
	v_mul_f32_e32 v17, 0xbfb8aa3b, v16
	v_mul_f32_e32 v146, v113, v8
	v_exp_f32_e32 v17, v17
	v_mul_f32_e32 v148, 0xbfb8aa3b, v146
	v_exp_f32_e32 v148, v148
	v_rcp_f32_e32 v13, v13
	v_add_f32_e32 v17, 1.0, v17
	v_rcp_f32_e32 v17, v17
	v_add_f32_e32 v148, 1.0, v148
	v_rcp_f32_e32 v148, v148
	v_mul_f32_e32 v13, v11, v13
	v_cndmask_b32_e64 v11, v11, v13, s[36:37]
	v_mul_f32_e32 v13, v16, v17
	v_cndmask_b32_e64 v13, v16, v13, s[36:37]
	v_mul_f32_e32 v16, v146, v148
	v_cndmask_b32_e64 v17, v146, v16, s[36:37]
	v_cvt_pk_bf16_f32 v16, v9, v11
	s_waitcnt vmcnt(1)
	v_mul_f32_e32 v9, v50, v6
	v_cvt_pk_bf16_f32 v17, v13, v17
	v_mul_f32_e32 v11, 0xbfb8aa3b, v9
	v_mul_f32_e32 v13, v51, v6
	v_exp_f32_e32 v11, v11
	v_mul_f32_e32 v146, 0xbfb8aa3b, v13
	v_exp_f32_e32 v146, v146
	ds_write2_b64 v7, v[14:15], v[16:17] offset0:76 offset1:78
	v_add_f32_e32 v7, 1.0, v11
	v_mul_f32_e32 v14, v52, v6
	v_rcp_f32_e32 v7, v7
	v_add_f32_e32 v11, 1.0, v146
	v_mul_f32_e32 v15, 0xbfb8aa3b, v14
	v_rcp_f32_e32 v11, v11
	v_exp_f32_e32 v15, v15
	v_mul_f32_e32 v7, v9, v7
	v_cndmask_b32_e64 v7, v9, v7, s[36:37]
	v_mul_f32_e32 v9, v13, v11
	v_add_f32_e32 v11, 1.0, v15
	v_mul_f32_e32 v15, v53, v6
	v_mul_f32_e32 v16, 0xbfb8aa3b, v15
	v_rcp_f32_e32 v11, v11
	v_exp_f32_e32 v16, v16
	v_cndmask_b32_e64 v9, v13, v9, s[36:37]
	v_mul_f32_e32 v11, v14, v11
	v_add_f32_e32 v13, 1.0, v16
	v_mul_f32_e32 v16, v54, v6
	v_cndmask_b32_e64 v11, v14, v11, s[36:37]
	v_mul_f32_e32 v14, 0xbfb8aa3b, v16
	v_rcp_f32_e32 v13, v13
	v_exp_f32_e32 v17, v14
	v_cvt_pk_bf16_f32 v14, v7, v9
	v_mul_f32_e32 v9, v55, v6
	v_mul_f32_e32 v13, v15, v13
	v_add_f32_e32 v7, 1.0, v17
	v_cndmask_b32_e64 v13, v15, v13, s[36:37]
	v_rcp_f32_e32 v7, v7
	v_mul_f32_e32 v15, 0xbfb8aa3b, v9
	v_exp_f32_e32 v17, v15
	v_cvt_pk_bf16_f32 v15, v11, v13
	v_mul_f32_e32 v7, v16, v7
	v_mul_f32_e32 v13, v56, v6
	v_cndmask_b32_e64 v7, v16, v7, s[36:37]
	v_add_f32_e32 v11, 1.0, v17
	v_mul_f32_e32 v16, 0xbfb8aa3b, v13
	v_mul_f32_e32 v17, v57, v6
	v_exp_f32_e32 v16, v16
	v_mul_f32_e32 v146, 0xbfb8aa3b, v17
	v_exp_f32_e32 v146, v146
	v_rcp_f32_e32 v11, v11
	v_add_f32_e32 v16, 1.0, v16
; __device__ __forceinline__ unsigned pk2(float lo, float hi) { f32x2_t v = {lo, hi}; bf16x2_t b = __builtin_convertvector(v, bf16x2_t); return __builtin_bit_cast(unsigned, b); }
; __device__ __forceinline__ float fsigmoid(float x) { return __builtin_amdgcn_rcpf(1.f + fexp(-x)); }
;     ...
;         for (int tt = 0; tt < 4; ++tt) {
;           u16* srow = stg + (tt * 32 + l31) * LD;
; #pragma unroll
;           for (int ct = 0; ct < 2; ++ct)
; #pragma unroll
;             for (int rq = 0; rq < 4; ++rq) {
;               float v[4];
; #pragma unroll
;               for (int e = 0; e < 4; ++e) { v[e] = acc[ct][tt][rq * 4 + e] * rsv[tt]; if (act) v[e] = v[e] * fsigmoid(v[e]); }
;               u32x2 w; w.x = pk2(v[0], v[1]); w.y = pk2(v[2], v[3]);
;               *(u32x2*)(srow + ct * 32 + 8 * rq + 4 * h) = w;
	v_rcp_f32_e32 v16, v16
	v_add_f32_e32 v146, 1.0, v146
	v_rcp_f32_e32 v146, v146
	v_mul_f32_e32 v11, v9, v11
	v_cndmask_b32_e64 v9, v9, v11, s[36:37]
	v_mul_f32_e32 v11, v13, v16
	v_cndmask_b32_e64 v11, v13, v11, s[36:37]
	v_mul_f32_e32 v13, v17, v146
	v_cndmask_b32_e64 v13, v17, v13, s[36:37]
	v_cvt_pk_bf16_f32 v16, v7, v9
	v_mul_f32_e32 v9, v58, v6
	v_cvt_pk_bf16_f32 v17, v11, v13
	v_mul_f32_e32 v11, 0xbfb8aa3b, v9
	v_mul_f32_e32 v13, v59, v6
	v_exp_f32_e32 v11, v11
	v_mul_f32_e32 v146, 0xbfb8aa3b, v13
	v_exp_f32_e32 v146, v146
	v_add_u32_e32 v7, 0x2000, v2
	ds_write2_b64 v7, v[14:15], v[16:17] offset0:128 offset1:130
	v_add_f32_e32 v11, 1.0, v11
	v_mul_f32_e32 v15, v60, v6
	v_rcp_f32_e32 v11, v11
	v_add_f32_e32 v14, 1.0, v146
	v_mul_f32_e32 v16, 0xbfb8aa3b, v15
	v_rcp_f32_e32 v14, v14
	v_exp_f32_e32 v16, v16
	v_mul_f32_e32 v11, v9, v11
	v_cndmask_b32_e64 v9, v9, v11, s[36:37]
	v_mul_f32_e32 v11, v13, v14
	v_add_f32_e32 v14, 1.0, v16
	v_mul_f32_e32 v16, v61, v6
	v_mul_f32_e32 v17, 0xbfb8aa3b, v16
	v_rcp_f32_e32 v14, v14
	v_exp_f32_e32 v17, v17
	v_cndmask_b32_e64 v11, v13, v11, s[36:37]
	v_add_u32_e32 v2, 0x3000, v2
	v_mul_f32_e32 v13, v15, v14
	v_add_f32_e32 v14, 1.0, v17
	v_mul_f32_e32 v17, v62, v6
	v_cndmask_b32_e64 v13, v15, v13, s[36:37]
	v_rcp_f32_e32 v14, v14
	v_mul_f32_e32 v15, 0xbfb8aa3b, v17
	v_exp_f32_e32 v15, v15
	v_mul_f32_e32 v14, v16, v14
	v_cndmask_b32_e64 v16, v16, v14, s[36:37]
	v_cvt_pk_bf16_f32 v14, v9, v11
	v_add_f32_e32 v9, 1.0, v15
	v_mul_f32_e32 v11, v63, v6
	v_rcp_f32_e32 v9, v9
	v_mul_f32_e32 v15, 0xbfb8aa3b, v11
	v_exp_f32_e32 v146, v15
	v_cvt_pk_bf16_f32 v15, v13, v16
	v_mul_f32_e32 v9, v17, v9
	v_mul_f32_e32 v16, v64, v6
	v_cndmask_b32_e64 v9, v17, v9, s[36:37]
	v_add_f32_e32 v13, 1.0, v146
	v_mul_f32_e32 v17, 0xbfb8aa3b, v16
	v_mul_f32_e32 v146, v65, v6
	v_exp_f32_e32 v17, v17
	v_mul_f32_e32 v148, 0xbfb8aa3b, v146
	v_exp_f32_e32 v148, v148
	v_rcp_f32_e32 v13, v13
	v_add_f32_e32 v17, 1.0, v17
	v_rcp_f32_e32 v17, v17
	v_add_f32_e32 v148, 1.0, v148
	v_rcp_f32_e32 v148, v148
	v_mul_f32_e32 v13, v11, v13
	v_cndmask_b32_e64 v11, v11, v13, s[36:37]
	v_mul_f32_e32 v13, v16, v17
	v_cndmask_b32_e64 v13, v16, v13, s[36:37]
	v_mul_f32_e32 v16, v146, v148
	v_cndmask_b32_e64 v17, v146, v16, s[36:37]
	v_cvt_pk_bf16_f32 v16, v9, v11
	v_mul_f32_e32 v9, v66, v6
	v_cvt_pk_bf16_f32 v17, v13, v17
	v_mul_f32_e32 v11, 0xbfb8aa3b, v9
	v_mul_f32_e32 v13, v67, v6
	v_exp_f32_e32 v11, v11
	v_mul_f32_e32 v146, 0xbfb8aa3b, v13
	v_exp_f32_e32 v146, v146
	ds_write2_b64 v7, v[14:15], v[16:17] offset0:132 offset1:134
	v_add_f32_e32 v11, 1.0, v11
	v_mul_f32_e32 v15, v68, v6
	v_rcp_f32_e32 v11, v11
	v_add_f32_e32 v14, 1.0, v146
	v_mul_f32_e32 v16, 0xbfb8aa3b, v15
	v_rcp_f32_e32 v14, v14
	v_exp_f32_e32 v16, v16
	v_mul_f32_e32 v11, v9, v11
	v_cndmask_b32_e64 v9, v9, v11, s[36:37]
	v_mul_f32_e32 v11, v13, v14
	v_add_f32_e32 v14, 1.0, v16
	v_mul_f32_e32 v16, v69, v6
	v_mul_f32_e32 v17, 0xbfb8aa3b, v16
	v_rcp_f32_e32 v14, v14
	v_exp_f32_e32 v17, v17
	v_cndmask_b32_e64 v11, v13, v11, s[36:37]
	v_mul_f32_e32 v13, v15, v14
	v_add_f32_e32 v14, 1.0, v17
	v_mul_f32_e32 v17, v70, v6
	v_cndmask_b32_e64 v13, v15, v13, s[36:37]
	v_rcp_f32_e32 v14, v14
	v_mul_f32_e32 v15, 0xbfb8aa3b, v17
	v_exp_f32_e32 v15, v15
	v_mul_f32_e32 v14, v16, v14
	v_cndmask_b32_e64 v16, v16, v14, s[36:37]
	v_cvt_pk_bf16_f32 v14, v9, v11
	v_add_f32_e32 v9, 1.0, v15
	v_mul_f32_e32 v11, v71, v6
	v_rcp_f32_e32 v9, v9
	v_mul_f32_e32 v15, 0xbfb8aa3b, v11
	v_exp_f32_e32 v146, v15
	v_cvt_pk_bf16_f32 v15, v13, v16
	v_mul_f32_e32 v9, v17, v9
	v_mul_f32_e32 v16, v72, v6
	v_cndmask_b32_e64 v9, v17, v9, s[36:37]
	v_add_f32_e32 v13, 1.0, v146
	v_mul_f32_e32 v17, 0xbfb8aa3b, v16
	v_mul_f32_e32 v146, v73, v6
	v_exp_f32_e32 v17, v17
	v_mul_f32_e32 v148, 0xbfb8aa3b, v146
	v_exp_f32_e32 v148, v148
	v_rcp_f32_e32 v13, v13
	v_add_f32_e32 v17, 1.0, v17
	v_rcp_f32_e32 v17, v17
	v_add_f32_e32 v148, 1.0, v148
	v_rcp_f32_e32 v148, v148
	v_mul_f32_e32 v13, v11, v13
	v_cndmask_b32_e64 v11, v11, v13, s[36:37]
	v_mul_f32_e32 v13, v16, v17
	v_cndmask_b32_e64 v13, v16, v13, s[36:37]
	v_mul_f32_e32 v16, v146, v148
	v_cndmask_b32_e64 v17, v146, v16, s[36:37]
	v_cvt_pk_bf16_f32 v16, v9, v11
	v_mul_f32_e32 v9, v74, v6
	v_cvt_pk_bf16_f32 v17, v13, v17
	v_mul_f32_e32 v11, 0xbfb8aa3b, v9
	v_mul_f32_e32 v13, v75, v6
	v_exp_f32_e32 v11, v11
	v_mul_f32_e32 v146, 0xbfb8aa3b, v13
	v_exp_f32_e32 v146, v146
	ds_write2_b64 v7, v[14:15], v[16:17] offset0:136 offset1:138
	v_add_f32_e32 v11, 1.0, v11
	v_mul_f32_e32 v15, v76, v6
	v_rcp_f32_e32 v11, v11
	v_add_f32_e32 v14, 1.0, v146
	v_mul_f32_e32 v16, 0xbfb8aa3b, v15
	v_rcp_f32_e32 v14, v14
	v_exp_f32_e32 v16, v16
	v_mul_f32_e32 v11, v9, v11
	v_cndmask_b32_e64 v9, v9, v11, s[36:37]
	v_mul_f32_e32 v11, v13, v14
	v_add_f32_e32 v14, 1.0, v16
	v_mul_f32_e32 v16, v77, v6
	v_mul_f32_e32 v17, 0xbfb8aa3b, v16
	v_rcp_f32_e32 v14, v14
	v_exp_f32_e32 v17, v17
	v_cndmask_b32_e64 v11, v13, v11, s[36:37]
	v_mul_f32_e32 v13, v15, v14
	v_add_f32_e32 v14, 1.0, v17
	v_mul_f32_e32 v17, v78, v6
	v_cndmask_b32_e64 v13, v15, v13, s[36:37]
	v_rcp_f32_e32 v14, v14
	v_mul_f32_e32 v15, 0xbfb8aa3b, v17
	v_exp_f32_e32 v15, v15
	v_mul_f32_e32 v14, v16, v14
	v_cndmask_b32_e64 v16, v16, v14, s[36:37]
	v_cvt_pk_bf16_f32 v14, v9, v11
	v_add_f32_e32 v9, 1.0, v15
	v_mul_f32_e32 v11, v79, v6
	v_rcp_f32_e32 v9, v9
	v_mul_f32_e32 v15, 0xbfb8aa3b, v11
	v_exp_f32_e32 v146, v15
	v_cvt_pk_bf16_f32 v15, v13, v16
	v_mul_f32_e32 v9, v17, v9
	v_mul_f32_e32 v16, v80, v6
	v_cndmask_b32_e64 v9, v17, v9, s[36:37]
	v_add_f32_e32 v13, 1.0, v146
	v_mul_f32_e32 v17, 0xbfb8aa3b, v16
	v_mul_f32_e32 v146, v81, v6
	v_exp_f32_e32 v17, v17
	v_mul_f32_e32 v148, 0xbfb8aa3b, v146
	v_exp_f32_e32 v148, v148
	v_rcp_f32_e32 v13, v13
	v_add_f32_e32 v17, 1.0, v17
	v_rcp_f32_e32 v17, v17
	v_add_f32_e32 v148, 1.0, v148
	v_rcp_f32_e32 v148, v148
	v_mul_f32_e32 v13, v11, v13
	v_cndmask_b32_e64 v11, v11, v13, s[36:37]
	v_mul_f32_e32 v13, v16, v17
	v_cndmask_b32_e64 v13, v16, v13, s[36:37]
	v_mul_f32_e32 v16, v146, v148
	v_cndmask_b32_e64 v17, v146, v16, s[36:37]
	v_cvt_pk_bf16_f32 v16, v9, v11
	s_waitcnt vmcnt(0)
; __device__ __forceinline__ unsigned pk2(float lo, float hi) { f32x2_t v = {lo, hi}; bf16x2_t b = __builtin_convertvector(v, bf16x2_t); return __builtin_bit_cast(unsigned, b); }
; __device__ __forceinline__ float fsigmoid(float x) { return __builtin_amdgcn_rcpf(1.f + fexp(-x)); }
;     ...
;         for (int tt = 0; tt < 4; ++tt) {
;           u16* srow = stg + (tt * 32 + l31) * LD;
; #pragma unroll
;           for (int ct = 0; ct < 2; ++ct)
; #pragma unroll
;             for (int rq = 0; rq < 4; ++rq) {
;               float v[4];
; #pragma unroll
;               for (int e = 0; e < 4; ++e) { v[e] = acc[ct][tt][rq * 4 + e] * rsv[tt]; if (act) v[e] = v[e] * fsigmoid(v[e]); }
;               u32x2 w; w.x = pk2(v[0], v[1]); w.y = pk2(v[2], v[3]);
;               *(u32x2*)(srow + ct * 32 + 8 * rq + 4 * h) = w;
	v_mul_f32_e32 v9, v18, v4
	v_cvt_pk_bf16_f32 v17, v13, v17
	v_mul_f32_e32 v11, 0xbfb8aa3b, v9
	v_mul_f32_e32 v13, v19, v4
	v_exp_f32_e32 v11, v11
	v_mul_f32_e32 v146, 0xbfb8aa3b, v13
	v_exp_f32_e32 v146, v146
	ds_write2_b64 v7, v[14:15], v[16:17] offset0:140 offset1:142
	v_add_f32_e32 v7, 1.0, v11
	v_mul_f32_e32 v14, v20, v4
	v_rcp_f32_e32 v7, v7
	v_add_f32_e32 v11, 1.0, v146
	v_mul_f32_e32 v15, 0xbfb8aa3b, v14
	v_rcp_f32_e32 v11, v11
	v_exp_f32_e32 v15, v15
	v_mul_f32_e32 v7, v9, v7
	v_cndmask_b32_e64 v7, v9, v7, s[36:37]
	v_mul_f32_e32 v9, v13, v11
	v_add_f32_e32 v11, 1.0, v15
	v_mul_f32_e32 v15, v21, v4
	v_mul_f32_e32 v16, 0xbfb8aa3b, v15
	v_rcp_f32_e32 v11, v11
	v_exp_f32_e32 v16, v16
	v_cndmask_b32_e64 v9, v13, v9, s[36:37]
	v_mul_f32_e32 v11, v14, v11
	v_add_f32_e32 v13, 1.0, v16
	v_mul_f32_e32 v16, v22, v4
	v_cndmask_b32_e64 v11, v14, v11, s[36:37]
	v_mul_f32_e32 v14, 0xbfb8aa3b, v16
	v_rcp_f32_e32 v13, v13
	v_exp_f32_e32 v17, v14
	v_cvt_pk_bf16_f32 v14, v7, v9
	v_mul_f32_e32 v9, v23, v4
	v_mul_f32_e32 v13, v15, v13
	v_add_f32_e32 v7, 1.0, v17
	v_cndmask_b32_e64 v13, v15, v13, s[36:37]
	v_rcp_f32_e32 v7, v7
	v_mul_f32_e32 v15, 0xbfb8aa3b, v9
	v_exp_f32_e32 v17, v15
	v_cvt_pk_bf16_f32 v15, v11, v13
	v_mul_f32_e32 v7, v16, v7
	v_mul_f32_e32 v13, v24, v4
	v_cndmask_b32_e64 v7, v16, v7, s[36:37]
	v_add_f32_e32 v11, 1.0, v17
	v_mul_f32_e32 v16, 0xbfb8aa3b, v13
	v_mul_f32_e32 v17, v25, v4
	v_exp_f32_e32 v16, v16
	v_mul_f32_e32 v146, 0xbfb8aa3b, v17
	v_exp_f32_e32 v146, v146
	v_rcp_f32_e32 v11, v11
	v_add_f32_e32 v16, 1.0, v16
	v_rcp_f32_e32 v16, v16
	v_add_f32_e32 v146, 1.0, v146
	v_rcp_f32_e32 v146, v146
	v_mul_f32_e32 v11, v9, v11
	v_cndmask_b32_e64 v9, v9, v11, s[36:37]
	v_mul_f32_e32 v11, v13, v16
	v_cndmask_b32_e64 v11, v13, v11, s[36:37]
	v_mul_f32_e32 v13, v17, v146
	v_cndmask_b32_e64 v13, v17, v13, s[36:37]
	v_cvt_pk_bf16_f32 v16, v7, v9
	v_mul_f32_e32 v7, v26, v4
	v_cvt_pk_bf16_f32 v17, v11, v13
	v_mul_f32_e32 v9, 0xbfb8aa3b, v7
	v_mul_f32_e32 v11, v27, v4
	v_exp_f32_e32 v9, v9
	v_mul_f32_e32 v13, 0xbfb8aa3b, v11
	v_exp_f32_e32 v13, v13
	ds_write2_b64 v2, v[14:15], v[16:17] offset0:192 offset1:194
	v_add_f32_e32 v9, 1.0, v9
	v_mul_f32_e32 v14, v28, v4
	v_rcp_f32_e32 v9, v9
	v_add_f32_e32 v13, 1.0, v13
	v_mul_f32_e32 v15, 0xbfb8aa3b, v14
	v_rcp_f32_e32 v13, v13
	v_exp_f32_e32 v15, v15
	v_mul_f32_e32 v9, v7, v9
	v_cndmask_b32_e64 v7, v7, v9, s[36:37]
	v_mul_f32_e32 v9, v11, v13
	v_add_f32_e32 v13, 1.0, v15
	v_mul_f32_e32 v15, v29, v4
	v_mul_f32_e32 v16, 0xbfb8aa3b, v15
	v_rcp_f32_e32 v13, v13
	v_exp_f32_e32 v16, v16
	v_cndmask_b32_e64 v9, v11, v9, s[36:37]
	v_mul_f32_e32 v11, v14, v13
	v_add_f32_e32 v13, 1.0, v16
	v_mul_f32_e32 v16, v30, v4
	v_cndmask_b32_e64 v11, v14, v11, s[36:37]
	v_mul_f32_e32 v14, 0xbfb8aa3b, v16
	v_rcp_f32_e32 v13, v13
	v_exp_f32_e32 v17, v14
	v_cvt_pk_bf16_f32 v14, v7, v9
	v_mul_f32_e32 v9, v31, v4
	v_mul_f32_e32 v13, v15, v13
	v_add_f32_e32 v7, 1.0, v17
	v_cndmask_b32_e64 v13, v15, v13, s[36:37]
	v_rcp_f32_e32 v7, v7
	v_mul_f32_e32 v15, 0xbfb8aa3b, v9
	v_exp_f32_e32 v17, v15
	v_cvt_pk_bf16_f32 v15, v11, v13
	v_mul_f32_e32 v7, v16, v7
	v_mul_f32_e32 v13, v32, v4
	v_cndmask_b32_e64 v7, v16, v7, s[36:37]
	v_add_f32_e32 v11, 1.0, v17
	v_mul_f32_e32 v16, 0xbfb8aa3b, v13
	v_mul_f32_e32 v17, v33, v4
	v_exp_f32_e32 v16, v16
	v_mul_f32_e32 v146, 0xbfb8aa3b, v17
	v_exp_f32_e32 v146, v146
	v_rcp_f32_e32 v11, v11
	v_add_f32_e32 v16, 1.0, v16
	v_rcp_f32_e32 v16, v16
	v_add_f32_e32 v146, 1.0, v146
	v_rcp_f32_e32 v146, v146
	v_mul_f32_e32 v11, v9, v11
	v_cndmask_b32_e64 v9, v9, v11, s[36:37]
	v_mul_f32_e32 v11, v13, v16
	v_cndmask_b32_e64 v11, v13, v11, s[36:37]
	v_mul_f32_e32 v13, v17, v146
	v_cndmask_b32_e64 v13, v17, v13, s[36:37]
	v_cvt_pk_bf16_f32 v16, v7, v9
	v_mul_f32_e32 v7, v34, v4
	v_cvt_pk_bf16_f32 v17, v11, v13
	v_mul_f32_e32 v9, 0xbfb8aa3b, v7
	v_mul_f32_e32 v11, v35, v4
	v_exp_f32_e32 v9, v9
	v_mul_f32_e32 v13, 0xbfb8aa3b, v11
	v_exp_f32_e32 v13, v13
	ds_write2_b64 v2, v[14:15], v[16:17] offset0:196 offset1:198
	v_add_f32_e32 v9, 1.0, v9
	v_mul_f32_e32 v14, v36, v4
	v_rcp_f32_e32 v9, v9
	v_add_f32_e32 v13, 1.0, v13
	v_mul_f32_e32 v15, 0xbfb8aa3b, v14
	v_rcp_f32_e32 v13, v13
	v_exp_f32_e32 v15, v15
	v_mul_f32_e32 v9, v7, v9
	v_cndmask_b32_e64 v7, v7, v9, s[36:37]
	v_mul_f32_e32 v9, v11, v13
	v_add_f32_e32 v13, 1.0, v15
	v_mul_f32_e32 v15, v37, v4
	v_mul_f32_e32 v16, 0xbfb8aa3b, v15
	v_rcp_f32_e32 v13, v13
	v_exp_f32_e32 v16, v16
	v_cndmask_b32_e64 v9, v11, v9, s[36:37]
	v_mul_f32_e32 v11, v14, v13
	v_add_f32_e32 v13, 1.0, v16
	v_mul_f32_e32 v16, v38, v4
	v_cndmask_b32_e64 v11, v14, v11, s[36:37]
	v_mul_f32_e32 v14, 0xbfb8aa3b, v16
	v_rcp_f32_e32 v13, v13
	v_exp_f32_e32 v17, v14
	v_cvt_pk_bf16_f32 v14, v7, v9
	v_mul_f32_e32 v9, v39, v4
	v_mul_f32_e32 v13, v15, v13
	v_add_f32_e32 v7, 1.0, v17
	v_cndmask_b32_e64 v13, v15, v13, s[36:37]
	v_rcp_f32_e32 v7, v7
	v_mul_f32_e32 v15, 0xbfb8aa3b, v9
	v_exp_f32_e32 v17, v15
	v_cvt_pk_bf16_f32 v15, v11, v13
	v_mul_f32_e32 v7, v16, v7
	v_mul_f32_e32 v13, v40, v4
	v_cndmask_b32_e64 v7, v16, v7, s[36:37]
	v_add_f32_e32 v11, 1.0, v17
	v_mul_f32_e32 v16, 0xbfb8aa3b, v13
	v_mul_f32_e32 v17, v41, v4
	v_exp_f32_e32 v16, v16
	v_mul_f32_e32 v146, 0xbfb8aa3b, v17
	v_exp_f32_e32 v146, v146
	v_rcp_f32_e32 v11, v11
	v_add_f32_e32 v16, 1.0, v16
	v_rcp_f32_e32 v16, v16
	v_add_f32_e32 v146, 1.0, v146
	v_rcp_f32_e32 v146, v146
	v_mul_f32_e32 v11, v9, v11
	v_cndmask_b32_e64 v9, v9, v11, s[36:37]
	v_mul_f32_e32 v11, v13, v16
	v_cndmask_b32_e64 v11, v13, v11, s[36:37]
	v_mul_f32_e32 v13, v17, v146
	v_cndmask_b32_e64 v13, v17, v13, s[36:37]
	v_cvt_pk_bf16_f32 v16, v7, v9
	v_mul_f32_e32 v7, v42, v4
; __device__ __forceinline__ unsigned pk2(float lo, float hi) { f32x2_t v = {lo, hi}; bf16x2_t b = __builtin_convertvector(v, bf16x2_t); return __builtin_bit_cast(unsigned, b); }
; __device__ __forceinline__ float fsigmoid(float x) { return __builtin_amdgcn_rcpf(1.f + fexp(-x)); }
;     ...
;       auto flush_rows = [&](u16* gbase, size_t ldd) {
; #pragma unroll
;         for (int it = 0; it < 16; ++it) {
;           const int r = it * 8 + (lane >> 3), ch = lane & 7;
;           *(u32x4*)(gbase + (size_t)r * ldd + ch * 8) = *(const u32x4*)(stg + r * LD + ch * 8);
;         }
;     ...
;               for (int e = 0; e < 4; ++e) { v[e] = acc[ct][tt][rq * 4 + e] * rsv[tt]; if (act) v[e] = v[e] * fsigmoid(v[e]); }
;               u32x2 w; w.x = pk2(v[0], v[1]); w.y = pk2(v[2], v[3]);
;               *(u32x2*)(srow + ct * 32 + 8 * rq + 4 * h) = w;
;             }
;         }
;         flush_rows(dst + (size_t)(m0 + wr * 128) * ldd + c0, (size_t)ldd);
	v_cvt_pk_bf16_f32 v17, v11, v13
	v_mul_f32_e32 v9, 0xbfb8aa3b, v7
	v_mul_f32_e32 v11, v43, v4
	v_exp_f32_e32 v9, v9
	v_mul_f32_e32 v13, 0xbfb8aa3b, v11
	v_exp_f32_e32 v13, v13
	ds_write2_b64 v2, v[14:15], v[16:17] offset0:200 offset1:202
	v_add_f32_e32 v9, 1.0, v9
	v_mul_f32_e32 v14, v44, v4
	v_rcp_f32_e32 v9, v9
	v_add_f32_e32 v13, 1.0, v13
	v_mul_f32_e32 v15, 0xbfb8aa3b, v14
	v_rcp_f32_e32 v13, v13
	v_exp_f32_e32 v15, v15
	v_mul_f32_e32 v9, v7, v9
	v_cndmask_b32_e64 v7, v7, v9, s[36:37]
	v_mul_f32_e32 v9, v11, v13
	v_add_f32_e32 v13, 1.0, v15
	v_mul_f32_e32 v15, v45, v4
	v_mul_f32_e32 v16, 0xbfb8aa3b, v15
	v_rcp_f32_e32 v13, v13
	v_exp_f32_e32 v16, v16
	v_cndmask_b32_e64 v9, v11, v9, s[36:37]
	v_mul_f32_e32 v11, v14, v13
	v_add_f32_e32 v13, 1.0, v16
	v_mul_f32_e32 v16, v46, v4
	v_cndmask_b32_e64 v11, v14, v11, s[36:37]
	v_mul_f32_e32 v14, 0xbfb8aa3b, v16
	v_rcp_f32_e32 v13, v13
	v_exp_f32_e32 v17, v14
	v_cvt_pk_bf16_f32 v14, v7, v9
	v_mul_f32_e32 v9, v47, v4
	v_mul_f32_e32 v13, v15, v13
	v_add_f32_e32 v7, 1.0, v17
	v_cndmask_b32_e64 v13, v15, v13, s[36:37]
	v_rcp_f32_e32 v7, v7
	v_mul_f32_e32 v15, 0xbfb8aa3b, v9
	v_exp_f32_e32 v17, v15
	v_cvt_pk_bf16_f32 v15, v11, v13
	v_mul_f32_e32 v7, v16, v7
	v_mul_f32_e32 v13, v48, v4
	v_cndmask_b32_e64 v7, v16, v7, s[36:37]
	v_add_f32_e32 v11, 1.0, v17
	v_mul_f32_e32 v16, 0xbfb8aa3b, v13
	v_mul_f32_e32 v17, v49, v4
	v_exp_f32_e32 v16, v16
	v_mul_f32_e32 v146, 0xbfb8aa3b, v17
	v_exp_f32_e32 v146, v146
	v_rcp_f32_e32 v11, v11
	v_add_f32_e32 v16, 1.0, v16
	v_rcp_f32_e32 v16, v16
	v_add_f32_e32 v146, 1.0, v146
	v_rcp_f32_e32 v146, v146
	v_mul_f32_e32 v11, v9, v11
	v_cndmask_b32_e64 v9, v9, v11, s[36:37]
	v_mul_f32_e32 v11, v13, v16
	v_cndmask_b32_e64 v11, v13, v11, s[36:37]
	v_mul_f32_e32 v13, v17, v146
	v_cndmask_b32_e64 v13, v17, v13, s[36:37]
	s_mul_hi_i32 s37, s34, s31
	s_mul_i32 s36, s34, s31
	s_lshl_b64 s[36:37], s[36:37], 1
	v_cvt_pk_bf16_f32 v16, v7, v9
	v_cvt_pk_bf16_f32 v17, v11, v13
	s_waitcnt lgkmcnt(0)
	s_add_u32 s31, s38, s36
	v_lshrrev_b32_e32 v7, 3, v147
	v_lshlrev_b32_e32 v9, 4, v225
	ds_write2_b64 v2, v[14:15], v[16:17] offset0:204 offset1:206
	s_addc_u32 s35, s39, s37
	s_lshl_b64 s[36:37], s[20:21], 1
	v_mul_u32_u24_e32 v2, 0x90, v7
	v_and_b32_e32 v152, 0x70, v9
	s_add_u32 s36, s31, s36
	v_add3_u32 v9, s7, v2, v152
	v_mul_u32_u24_e32 v2, s34, v7
	s_addc_u32 s37, s35, s37
	ds_read_b128 v[14:17], v9
	v_lshlrev_b32_e32 v2, 1, v2
	v_lshl_add_u64 v[148:149], s[36:37], 0, v[2:3]
	v_lshl_add_u64 v[154:155], v[148:149], 0, v[152:153]
	ds_read_b128 v[148:151], v9 offset:1152
	v_or_b32_e32 v2, 8, v7
	v_mul_u32_u24_e32 v2, s34, v2
	v_lshlrev_b32_e32 v2, 1, v2
	s_waitcnt lgkmcnt(1)
	global_store_dwordx4 v[154:155], v[14:17], off nt
	s_nop 1
	v_lshl_add_u64 v[14:15], s[36:37], 0, v[2:3]
	v_or_b32_e32 v2, 16, v7
	v_lshl_add_u64 v[14:15], v[14:15], 0, v[152:153]
	v_mul_u32_u24_e32 v2, s34, v2
	s_waitcnt lgkmcnt(0)
	global_store_dwordx4 v[14:15], v[148:151], off nt
	ds_read_b128 v[14:17], v9 offset:2304
	v_lshlrev_b32_e32 v2, 1, v2
	v_lshl_add_u64 v[148:149], s[36:37], 0, v[2:3]
	v_lshl_add_u64 v[154:155], v[148:149], 0, v[152:153]
	ds_read_b128 v[148:151], v9 offset:3456
	v_or_b32_e32 v2, 24, v7
	v_mul_u32_u24_e32 v2, s34, v2
	v_lshlrev_b32_e32 v2, 1, v2
	s_waitcnt lgkmcnt(1)
	global_store_dwordx4 v[154:155], v[14:17], off nt
	s_nop 1
	v_lshl_add_u64 v[14:15], s[36:37], 0, v[2:3]
	v_or_b32_e32 v2, 32, v7
	v_lshl_add_u64 v[14:15], v[14:15], 0, v[152:153]
	v_mul_u32_u24_e32 v2, s34, v2
	s_waitcnt lgkmcnt(0)
;     ...
;       auto flush_rows = [&](u16* gbase, size_t ldd) {
; #pragma unroll
;         for (int it = 0; it < 16; ++it) {
;           const int r = it * 8 + (lane >> 3), ch = lane & 7;
;           *(u32x4*)(gbase + (size_t)r * ldd + ch * 8) = *(const u32x4*)(stg + r * LD + ch * 8);
;         }
	global_store_dwordx4 v[14:15], v[148:151], off nt
	ds_read_b128 v[14:17], v9 offset:4608
	v_lshlrev_b32_e32 v2, 1, v2
	v_lshl_add_u64 v[148:149], s[36:37], 0, v[2:3]
	v_lshl_add_u64 v[154:155], v[148:149], 0, v[152:153]
	ds_read_b128 v[148:151], v9 offset:5760
	v_or_b32_e32 v2, 40, v7
	v_mul_u32_u24_e32 v2, s34, v2
	v_lshlrev_b32_e32 v2, 1, v2
	s_waitcnt lgkmcnt(1)
	global_store_dwordx4 v[154:155], v[14:17], off nt
	s_nop 1
	v_lshl_add_u64 v[14:15], s[36:37], 0, v[2:3]
	v_or_b32_e32 v2, 48, v7
	v_lshl_add_u64 v[14:15], v[14:15], 0, v[152:153]
	v_mul_u32_u24_e32 v2, s34, v2
	s_waitcnt lgkmcnt(0)
	global_store_dwordx4 v[14:15], v[148:151], off nt
	ds_read_b128 v[14:17], v9 offset:6912
	v_lshlrev_b32_e32 v2, 1, v2
	v_lshl_add_u64 v[148:149], s[36:37], 0, v[2:3]
	v_lshl_add_u64 v[154:155], v[148:149], 0, v[152:153]
	ds_read_b128 v[148:151], v9 offset:8064
	v_or_b32_e32 v2, 56, v7
	v_mul_u32_u24_e32 v2, s34, v2
	v_lshlrev_b32_e32 v2, 1, v2
	s_waitcnt lgkmcnt(1)
	global_store_dwordx4 v[154:155], v[14:17], off nt
	s_nop 1
	v_lshl_add_u64 v[14:15], s[36:37], 0, v[2:3]
	v_or_b32_e32 v2, 64, v7
	v_lshl_add_u64 v[14:15], v[14:15], 0, v[152:153]
	v_mul_u32_u24_e32 v2, s34, v2
	s_waitcnt lgkmcnt(0)
	global_store_dwordx4 v[14:15], v[148:151], off nt
	ds_read_b128 v[14:17], v9 offset:9216
	v_lshlrev_b32_e32 v2, 1, v2
	v_lshl_add_u64 v[148:149], s[36:37], 0, v[2:3]
	v_lshl_add_u64 v[154:155], v[148:149], 0, v[152:153]
	ds_read_b128 v[148:151], v9 offset:10368
	v_or_b32_e32 v2, 0x48, v7
	v_mul_u32_u24_e32 v2, s34, v2
	v_lshlrev_b32_e32 v2, 1, v2
	s_waitcnt lgkmcnt(1)
	global_store_dwordx4 v[154:155], v[14:17], off nt
	s_nop 1
	v_lshl_add_u64 v[14:15], s[36:37], 0, v[2:3]
	v_or_b32_e32 v2, 0x50, v7
	v_lshl_add_u64 v[14:15], v[14:15], 0, v[152:153]
	v_mul_u32_u24_e32 v2, s34, v2
	s_waitcnt lgkmcnt(0)
	global_store_dwordx4 v[14:15], v[148:151], off nt
	ds_read_b128 v[14:17], v9 offset:11520
	v_lshlrev_b32_e32 v2, 1, v2
	v_lshl_add_u64 v[148:149], s[36:37], 0, v[2:3]
	v_lshl_add_u64 v[154:155], v[148:149], 0, v[152:153]
	ds_read_b128 v[148:151], v9 offset:12672
	v_or_b32_e32 v2, 0x58, v7
	v_mul_u32_u24_e32 v2, s34, v2
	v_lshlrev_b32_e32 v2, 1, v2
	s_waitcnt lgkmcnt(1)
	global_store_dwordx4 v[154:155], v[14:17], off nt
	s_nop 1
	v_lshl_add_u64 v[14:15], s[36:37], 0, v[2:3]
	v_or_b32_e32 v2, 0x60, v7
	v_lshl_add_u64 v[14:15], v[14:15], 0, v[152:153]
	v_mul_u32_u24_e32 v2, s34, v2
	s_waitcnt lgkmcnt(0)
	global_store_dwordx4 v[14:15], v[148:151], off nt
	ds_read_b128 v[14:17], v9 offset:13824
	v_lshlrev_b32_e32 v2, 1, v2
	v_lshl_add_u64 v[148:149], s[36:37], 0, v[2:3]
	v_lshl_add_u64 v[154:155], v[148:149], 0, v[152:153]
	ds_read_b128 v[148:151], v9 offset:14976
	v_or_b32_e32 v2, 0x68, v7
	v_mul_u32_u24_e32 v2, s34, v2
	v_lshlrev_b32_e32 v2, 1, v2
	s_waitcnt lgkmcnt(1)
	global_store_dwordx4 v[154:155], v[14:17], off nt
	s_nop 1
	v_lshl_add_u64 v[14:15], s[36:37], 0, v[2:3]
	v_or_b32_e32 v2, 0x70, v7
	v_lshl_add_u64 v[14:15], v[14:15], 0, v[152:153]
	v_mul_u32_u24_e32 v2, s34, v2
	s_waitcnt lgkmcnt(0)
	global_store_dwordx4 v[14:15], v[148:151], off nt
	ds_read_b128 v[14:17], v9 offset:16128
	v_lshlrev_b32_e32 v2, 1, v2
	v_lshl_add_u64 v[148:149], s[36:37], 0, v[2:3]
	v_lshl_add_u64 v[154:155], v[148:149], 0, v[152:153]
	ds_read_b128 v[148:151], v9 offset:17280
	v_or_b32_e32 v2, 0x78, v7
	v_mul_u32_u24_e32 v2, s34, v2
	v_lshlrev_b32_e32 v2, 1, v2
	s_waitcnt lgkmcnt(1)
	global_store_dwordx4 v[154:155], v[14:17], off nt
	s_nop 1
	v_lshl_add_u64 v[14:15], s[36:37], 0, v[2:3]
	v_lshl_add_u64 v[14:15], v[14:15], 0, v[152:153]
	s_waitcnt lgkmcnt(0)
	global_store_dwordx4 v[14:15], v[148:151], off nt

; __device__ __forceinline__ unsigned pk2(float lo, float hi) { f32x2_t v = {lo, hi}; bf16x2_t b = __builtin_convertvector(v, bf16x2_t); return __builtin_bit_cast(unsigned, b); }
; __device__ __forceinline__ int rm32(int reg, int h) { return (reg & 3) + 8 * (reg >> 2) + 4 * h; }
;     ...
;         const int head = (nw - 1024) >> 6;
;         constexpr int VLD = 136;
; #pragma unroll
;         for (int tt = 0; tt < 4; ++tt)
; #pragma unroll
;           for (int ct = 0; ct < 2; ++ct)
; #pragma unroll
;             for (int r = 0; r < 16; r += 2) {
;               const unsigned w = pk2(acc[ct][tt][r] * rsv[tt], acc[ct][tt][r + 1] * rsv[tt]);
;               stg[(ct * 32 + rm32(r, h)) * VLD + tt * 32 + l31] = (u16)(w & 0xffffu);
;               stg[(ct * 32 + rm32(r + 1, h)) * VLD + tt * 32 + l31] = (u16)(w >> 16);
;             }
.LBB0_147:
	s_andn2_b64 vcc, exec, s[34:35]
	s_cbranch_vccnz .LBB0_149
	s_waitcnt vmcnt(3)
	v_pk_mul_f32 v[14:15], v[114:115], v[10:11] op_sel_hi:[1,0]
	v_mul_u32_u24_e32 v7, 0x440, v247
	v_lshlrev_b32_e32 v9, 1, v225
	v_cvt_pk_bf16_f32 v2, v14, v15
	v_add3_u32 v7, s7, v7, v9
	v_pk_mul_f32 v[14:15], v[116:117], v[10:11] op_sel_hi:[1,0]
	ds_write_b16 v7, v2
	ds_write_b16_d16_hi v7, v2 offset:272
	v_cvt_pk_bf16_f32 v2, v14, v15
	v_pk_mul_f32 v[14:15], v[118:119], v[10:11] op_sel_hi:[1,0]
	ds_write_b16 v7, v2 offset:544
	ds_write_b16_d16_hi v7, v2 offset:816
	v_cvt_pk_bf16_f32 v2, v14, v15
	v_pk_mul_f32 v[14:15], v[120:121], v[10:11] op_sel_hi:[1,0]
	ds_write_b16 v7, v2 offset:2176
	ds_write_b16_d16_hi v7, v2 offset:2448
	v_cvt_pk_bf16_f32 v2, v14, v15
	v_pk_mul_f32 v[14:15], v[122:123], v[10:11] op_sel_hi:[1,0]
	ds_write_b16 v7, v2 offset:2720
	ds_write_b16_d16_hi v7, v2 offset:2992
	v_cvt_pk_bf16_f32 v2, v14, v15
	v_pk_mul_f32 v[14:15], v[124:125], v[10:11] op_sel_hi:[1,0]
	ds_write_b16 v7, v2 offset:4352
	ds_write_b16_d16_hi v7, v2 offset:4624
	v_cvt_pk_bf16_f32 v2, v14, v15
	v_pk_mul_f32 v[14:15], v[126:127], v[10:11] op_sel_hi:[1,0]
	ds_write_b16 v7, v2 offset:4896
	ds_write_b16_d16_hi v7, v2 offset:5168
	v_cvt_pk_bf16_f32 v2, v14, v15
	v_pk_mul_f32 v[14:15], v[128:129], v[10:11] op_sel_hi:[1,0]
	ds_write_b16 v7, v2 offset:6528
	ds_write_b16_d16_hi v7, v2 offset:6800
	v_cvt_pk_bf16_f32 v2, v14, v15
	v_pk_mul_f32 v[14:15], v[130:131], v[10:11] op_sel_hi:[1,0]
	ds_write_b16 v7, v2 offset:7072
	ds_write_b16_d16_hi v7, v2 offset:7344
	v_cvt_pk_bf16_f32 v2, v14, v15
	v_pk_mul_f32 v[14:15], v[132:133], v[10:11] op_sel_hi:[1,0]
	ds_write_b16 v7, v2 offset:8704
	ds_write_b16_d16_hi v7, v2 offset:8976
	v_cvt_pk_bf16_f32 v2, v14, v15
	v_pk_mul_f32 v[14:15], v[134:135], v[10:11] op_sel_hi:[1,0]
	ds_write_b16 v7, v2 offset:9248
	ds_write_b16_d16_hi v7, v2 offset:9520
	v_cvt_pk_bf16_f32 v2, v14, v15
	v_pk_mul_f32 v[14:15], v[136:137], v[10:11] op_sel_hi:[1,0]
	ds_write_b16 v7, v2 offset:10880
	ds_write_b16_d16_hi v7, v2 offset:11152
	v_cvt_pk_bf16_f32 v2, v14, v15
	v_pk_mul_f32 v[14:15], v[138:139], v[10:11] op_sel_hi:[1,0]
	ds_write_b16 v7, v2 offset:11424
	ds_write_b16_d16_hi v7, v2 offset:11696
	v_cvt_pk_bf16_f32 v2, v14, v15
	v_pk_mul_f32 v[14:15], v[140:141], v[10:11] op_sel_hi:[1,0]
	ds_write_b16 v7, v2 offset:13056
	ds_write_b16_d16_hi v7, v2 offset:13328
	v_cvt_pk_bf16_f32 v2, v14, v15
	v_pk_mul_f32 v[14:15], v[142:143], v[10:11] op_sel_hi:[1,0]
	ds_write_b16 v7, v2 offset:13600
	ds_write_b16_d16_hi v7, v2 offset:13872
	v_cvt_pk_bf16_f32 v2, v14, v15
	v_pk_mul_f32 v[14:15], v[144:145], v[10:11] op_sel_hi:[1,0]
	ds_write_b16 v7, v2 offset:15232
	ds_write_b16_d16_hi v7, v2 offset:15504
	v_cvt_pk_bf16_f32 v2, v14, v15
	s_waitcnt vmcnt(2)
	v_pk_mul_f32 v[14:15], v[82:83], v[8:9] op_sel_hi:[1,0]
	ds_write_b16 v7, v2 offset:15776
	ds_write_b16_d16_hi v7, v2 offset:16048
	v_cvt_pk_bf16_f32 v2, v14, v15
	v_pk_mul_f32 v[14:15], v[84:85], v[8:9] op_sel_hi:[1,0]
	ds_write_b16 v7, v2 offset:64
	ds_write_b16_d16_hi v7, v2 offset:336
	v_cvt_pk_bf16_f32 v2, v14, v15
	v_pk_mul_f32 v[14:15], v[86:87], v[8:9] op_sel_hi:[1,0]
	ds_write_b16 v7, v2 offset:608
	ds_write_b16_d16_hi v7, v2 offset:880
	v_cvt_pk_bf16_f32 v2, v14, v15
	v_pk_mul_f32 v[14:15], v[88:89], v[8:9] op_sel_hi:[1,0]
	ds_write_b16 v7, v2 offset:2240
	ds_write_b16_d16_hi v7, v2 offset:2512
	v_cvt_pk_bf16_f32 v2, v14, v15
	v_pk_mul_f32 v[14:15], v[90:91], v[8:9] op_sel_hi:[1,0]
	ds_write_b16 v7, v2 offset:2784
	ds_write_b16_d16_hi v7, v2 offset:3056
	v_cvt_pk_bf16_f32 v2, v14, v15
	v_pk_mul_f32 v[14:15], v[92:93], v[8:9] op_sel_hi:[1,0]
	ds_write_b16 v7, v2 offset:4416
	ds_write_b16_d16_hi v7, v2 offset:4688
	v_cvt_pk_bf16_f32 v2, v14, v15
	v_pk_mul_f32 v[14:15], v[94:95], v[8:9] op_sel_hi:[1,0]
	ds_write_b16 v7, v2 offset:4960
	ds_write_b16_d16_hi v7, v2 offset:5232
	v_cvt_pk_bf16_f32 v2, v14, v15
	v_pk_mul_f32 v[14:15], v[96:97], v[8:9] op_sel_hi:[1,0]
	ds_write_b16 v7, v2 offset:6592
	ds_write_b16_d16_hi v7, v2 offset:6864
	v_cvt_pk_bf16_f32 v2, v14, v15
	v_pk_mul_f32 v[14:15], v[98:99], v[8:9] op_sel_hi:[1,0]
	ds_write_b16 v7, v2 offset:7136
	ds_write_b16_d16_hi v7, v2 offset:7408
	v_cvt_pk_bf16_f32 v2, v14, v15
	v_pk_mul_f32 v[14:15], v[100:101], v[8:9] op_sel_hi:[1,0]
	ds_write_b16 v7, v2 offset:8768
	ds_write_b16_d16_hi v7, v2 offset:9040
	v_cvt_pk_bf16_f32 v2, v14, v15
	v_pk_mul_f32 v[14:15], v[102:103], v[8:9] op_sel_hi:[1,0]
	ds_write_b16 v7, v2 offset:9312
	ds_write_b16_d16_hi v7, v2 offset:9584
	v_cvt_pk_bf16_f32 v2, v14, v15
	v_pk_mul_f32 v[14:15], v[104:105], v[8:9] op_sel_hi:[1,0]
	ds_write_b16 v7, v2 offset:10944
	ds_write_b16_d16_hi v7, v2 offset:11216
	v_cvt_pk_bf16_f32 v2, v14, v15
	v_pk_mul_f32 v[14:15], v[106:107], v[8:9] op_sel_hi:[1,0]
	ds_write_b16 v7, v2 offset:11488
	ds_write_b16_d16_hi v7, v2 offset:11760
	v_cvt_pk_bf16_f32 v2, v14, v15
	v_pk_mul_f32 v[14:15], v[108:109], v[8:9] op_sel_hi:[1,0]
	ds_write_b16 v7, v2 offset:13120
	ds_write_b16_d16_hi v7, v2 offset:13392
	v_cvt_pk_bf16_f32 v2, v14, v15
	v_pk_mul_f32 v[14:15], v[110:111], v[8:9] op_sel_hi:[1,0]
	ds_write_b16 v7, v2 offset:13664
	ds_write_b16_d16_hi v7, v2 offset:13936
	v_cvt_pk_bf16_f32 v2, v14, v15
	v_pk_mul_f32 v[14:15], v[112:113], v[8:9] op_sel_hi:[1,0]
	ds_write_b16 v7, v2 offset:15296
	ds_write_b16_d16_hi v7, v2 offset:15568
	v_cvt_pk_bf16_f32 v2, v14, v15
	s_waitcnt vmcnt(1)
; __device__ __forceinline__ unsigned pk2(float lo, float hi) { f32x2_t v = {lo, hi}; bf16x2_t b = __builtin_convertvector(v, bf16x2_t); return __builtin_bit_cast(unsigned, b); }
; __device__ __forceinline__ int rm32(int reg, int h) { return (reg & 3) + 8 * (reg >> 2) + 4 * h; }
;     ...
;         const int head = (nw - 1024) >> 6;
;         constexpr int VLD = 136;
; #pragma unroll
;         for (int tt = 0; tt < 4; ++tt)
; #pragma unroll
;           for (int ct = 0; ct < 2; ++ct)
; #pragma unroll
;             for (int r = 0; r < 16; r += 2) {
;               const unsigned w = pk2(acc[ct][tt][r] * rsv[tt], acc[ct][tt][r + 1] * rsv[tt]);
;               stg[(ct * 32 + rm32(r, h)) * VLD + tt * 32 + l31] = (u16)(w & 0xffffu);
;               stg[(ct * 32 + rm32(r + 1, h)) * VLD + tt * 32 + l31] = (u16)(w >> 16);
;             }
;         u16* gbase = p.Vt + (size_t)(bq * 8 + head) * 64 * SEQ + pos0;
; #pragma unroll
;         for (int it = 0; it < 16; ++it) {
;           const int d = it * 4 + (lane >> 4), ch = lane & 15;
;           *(u32x4*)(gbase + (size_t)d * SEQ + ch * 8) = *(const u32x4*)(stg + d * VLD + ch * 8);
;         }
	v_pk_mul_f32 v[14:15], v[50:51], v[6:7] op_sel_hi:[1,0]
	ds_write_b16 v7, v2 offset:15840
	ds_write_b16_d16_hi v7, v2 offset:16112
	v_cvt_pk_bf16_f32 v2, v14, v15
	v_pk_mul_f32 v[14:15], v[52:53], v[6:7] op_sel_hi:[1,0]
	ds_write_b16 v7, v2 offset:128
	ds_write_b16_d16_hi v7, v2 offset:400
	v_cvt_pk_bf16_f32 v2, v14, v15
	v_pk_mul_f32 v[14:15], v[54:55], v[6:7] op_sel_hi:[1,0]
	ds_write_b16 v7, v2 offset:672
	ds_write_b16_d16_hi v7, v2 offset:944
	v_cvt_pk_bf16_f32 v2, v14, v15
	v_pk_mul_f32 v[14:15], v[56:57], v[6:7] op_sel_hi:[1,0]
	ds_write_b16 v7, v2 offset:2304
	ds_write_b16_d16_hi v7, v2 offset:2576
	v_cvt_pk_bf16_f32 v2, v14, v15
	v_pk_mul_f32 v[14:15], v[58:59], v[6:7] op_sel_hi:[1,0]
	ds_write_b16 v7, v2 offset:2848
	ds_write_b16_d16_hi v7, v2 offset:3120
	v_cvt_pk_bf16_f32 v2, v14, v15
	v_pk_mul_f32 v[14:15], v[60:61], v[6:7] op_sel_hi:[1,0]
	ds_write_b16 v7, v2 offset:4480
	ds_write_b16_d16_hi v7, v2 offset:4752
	v_cvt_pk_bf16_f32 v2, v14, v15
	v_pk_mul_f32 v[14:15], v[62:63], v[6:7] op_sel_hi:[1,0]
	ds_write_b16 v7, v2 offset:5024
	ds_write_b16_d16_hi v7, v2 offset:5296
	v_cvt_pk_bf16_f32 v2, v14, v15
	v_pk_mul_f32 v[14:15], v[64:65], v[6:7] op_sel_hi:[1,0]
	ds_write_b16 v7, v2 offset:6656
	ds_write_b16_d16_hi v7, v2 offset:6928
	v_cvt_pk_bf16_f32 v2, v14, v15
	v_pk_mul_f32 v[14:15], v[66:67], v[6:7] op_sel_hi:[1,0]
	ds_write_b16 v7, v2 offset:7200
	ds_write_b16_d16_hi v7, v2 offset:7472
	v_cvt_pk_bf16_f32 v2, v14, v15
	v_pk_mul_f32 v[14:15], v[68:69], v[6:7] op_sel_hi:[1,0]
	ds_write_b16 v7, v2 offset:8832
	ds_write_b16_d16_hi v7, v2 offset:9104
	v_cvt_pk_bf16_f32 v2, v14, v15
	v_pk_mul_f32 v[14:15], v[70:71], v[6:7] op_sel_hi:[1,0]
	ds_write_b16 v7, v2 offset:9376
	ds_write_b16_d16_hi v7, v2 offset:9648
	v_cvt_pk_bf16_f32 v2, v14, v15
	v_pk_mul_f32 v[14:15], v[72:73], v[6:7] op_sel_hi:[1,0]
	ds_write_b16 v7, v2 offset:11008
	ds_write_b16_d16_hi v7, v2 offset:11280
	v_cvt_pk_bf16_f32 v2, v14, v15
	v_pk_mul_f32 v[14:15], v[74:75], v[6:7] op_sel_hi:[1,0]
	ds_write_b16 v7, v2 offset:11552
	ds_write_b16_d16_hi v7, v2 offset:11824
	v_cvt_pk_bf16_f32 v2, v14, v15
	v_pk_mul_f32 v[14:15], v[76:77], v[6:7] op_sel_hi:[1,0]
	ds_write_b16 v7, v2 offset:13184
	ds_write_b16_d16_hi v7, v2 offset:13456
	v_cvt_pk_bf16_f32 v2, v14, v15
	v_pk_mul_f32 v[14:15], v[78:79], v[6:7] op_sel_hi:[1,0]
	ds_write_b16 v7, v2 offset:13728
	ds_write_b16_d16_hi v7, v2 offset:14000
	v_cvt_pk_bf16_f32 v2, v14, v15
	v_pk_mul_f32 v[14:15], v[80:81], v[6:7] op_sel_hi:[1,0]
	ds_write_b16 v7, v2 offset:15360
	ds_write_b16_d16_hi v7, v2 offset:15632
	v_cvt_pk_bf16_f32 v2, v14, v15
	s_waitcnt vmcnt(0)
	v_pk_mul_f32 v[14:15], v[18:19], v[4:5] op_sel_hi:[1,0]
	ds_write_b16 v7, v2 offset:15904
	ds_write_b16_d16_hi v7, v2 offset:16176
	v_cvt_pk_bf16_f32 v2, v14, v15
	v_pk_mul_f32 v[14:15], v[20:21], v[4:5] op_sel_hi:[1,0]
	ds_write_b16 v7, v2 offset:192
	ds_write_b16_d16_hi v7, v2 offset:464
	v_cvt_pk_bf16_f32 v2, v14, v15
	v_pk_mul_f32 v[14:15], v[22:23], v[4:5] op_sel_hi:[1,0]
	ds_write_b16 v7, v2 offset:736
	ds_write_b16_d16_hi v7, v2 offset:1008
	v_cvt_pk_bf16_f32 v2, v14, v15
	v_pk_mul_f32 v[14:15], v[24:25], v[4:5] op_sel_hi:[1,0]
	ds_write_b16 v7, v2 offset:2368
	ds_write_b16_d16_hi v7, v2 offset:2640
	v_cvt_pk_bf16_f32 v2, v14, v15
	v_pk_mul_f32 v[14:15], v[26:27], v[4:5] op_sel_hi:[1,0]
	ds_write_b16 v7, v2 offset:2912
	ds_write_b16_d16_hi v7, v2 offset:3184
	v_cvt_pk_bf16_f32 v2, v14, v15
	v_pk_mul_f32 v[14:15], v[28:29], v[4:5] op_sel_hi:[1,0]
	ds_write_b16 v7, v2 offset:4544
	ds_write_b16_d16_hi v7, v2 offset:4816
	v_cvt_pk_bf16_f32 v2, v14, v15
	v_pk_mul_f32 v[14:15], v[30:31], v[4:5] op_sel_hi:[1,0]
	ds_write_b16 v7, v2 offset:5088
	ds_write_b16_d16_hi v7, v2 offset:5360
	v_cvt_pk_bf16_f32 v2, v14, v15
	v_pk_mul_f32 v[14:15], v[32:33], v[4:5] op_sel_hi:[1,0]
	ds_write_b16 v7, v2 offset:6720
	ds_write_b16_d16_hi v7, v2 offset:6992
	v_cvt_pk_bf16_f32 v2, v14, v15
	v_pk_mul_f32 v[14:15], v[34:35], v[4:5] op_sel_hi:[1,0]
	ds_write_b16 v7, v2 offset:7264
	ds_write_b16_d16_hi v7, v2 offset:7536
	v_cvt_pk_bf16_f32 v2, v14, v15
	v_pk_mul_f32 v[14:15], v[36:37], v[4:5] op_sel_hi:[1,0]
	ds_write_b16 v7, v2 offset:8896
	ds_write_b16_d16_hi v7, v2 offset:9168
	v_cvt_pk_bf16_f32 v2, v14, v15
	v_pk_mul_f32 v[14:15], v[38:39], v[4:5] op_sel_hi:[1,0]
	ds_write_b16 v7, v2 offset:9440
	ds_write_b16_d16_hi v7, v2 offset:9712
	v_cvt_pk_bf16_f32 v2, v14, v15
	v_pk_mul_f32 v[14:15], v[40:41], v[4:5] op_sel_hi:[1,0]
	ds_write_b16 v7, v2 offset:11072
	ds_write_b16_d16_hi v7, v2 offset:11344
	v_cvt_pk_bf16_f32 v2, v14, v15
	v_pk_mul_f32 v[14:15], v[42:43], v[4:5] op_sel_hi:[1,0]
	s_add_i32 s20, s64, 0xfffffc00
	ds_write_b16 v7, v2 offset:11616
	ds_write_b16_d16_hi v7, v2 offset:11888
	v_cvt_pk_bf16_f32 v2, v14, v15
	v_pk_mul_f32 v[14:15], v[44:45], v[4:5] op_sel_hi:[1,0]
	ds_write_b16 v7, v2 offset:13248
	ds_write_b16_d16_hi v7, v2 offset:13520
	v_cvt_pk_bf16_f32 v2, v14, v15
	v_pk_mul_f32 v[14:15], v[46:47], v[4:5] op_sel_hi:[1,0]
	s_ashr_i32 s20, s20, 6
	s_lshl_b32 s31, s63, 3
	ds_write_b16 v7, v2 offset:13792
	ds_write_b16_d16_hi v7, v2 offset:14064
	v_cvt_pk_bf16_f32 v2, v14, v15
	v_pk_mul_f32 v[14:15], v[48:49], v[4:5] op_sel_hi:[1,0]
	s_add_i32 s34, s20, s31
	ds_write_b16 v7, v2 offset:15424
	ds_write_b16_d16_hi v7, v2 offset:15696
	v_cvt_pk_bf16_f32 v2, v14, v15
	s_ashr_i32 s35, s34, 31
	ds_write_b16 v7, v2 offset:15968
	ds_write_b16_d16_hi v7, v2 offset:16240
	s_lshl_b64 s[34:35], s[34:35], 19
	v_lshrrev_b32_e32 v7, 4, v147
	v_lshlrev_b32_e32 v2, 4, v225
	s_add_u32 s20, s22, s34
	v_and_b32_e32 v2, 0xf0, v2
	v_mul_u32_u24_e32 v9, 0x110, v7
	s_addc_u32 s36, s23, s35
	s_ashr_i32 s31, s30, 31
	v_add3_u32 v9, s7, v2, v9
	s_lshl_b64 s[34:35], s[30:31], 1
	ds_read_b128 v[14:17], v9
	ds_read_b128 v[148:151], v9 offset:1088
	s_add_u32 s34, s20, s34
	s_addc_u32 s35, s36, s35
	v_lshl_add_u64 v[152:153], s[34:35], 0, v[2:3]
	v_lshlrev_b32_e32 v2, 13, v7
	v_lshl_add_u64 v[154:155], v[152:153], 0, v[2:3]
	s_waitcnt lgkmcnt(1)
;     ...
;         u16* gbase = p.Vt + (size_t)(bq * 8 + head) * 64 * SEQ + pos0;
; #pragma unroll
;         for (int it = 0; it < 16; ++it) {
;           const int d = it * 4 + (lane >> 4), ch = lane & 15;
;           *(u32x4*)(gbase + (size_t)d * SEQ + ch * 8) = *(const u32x4*)(stg + d * VLD + ch * 8);
;         }
	global_store_dwordx4 v[154:155], v[14:17], off nt
	s_nop 1
	v_or_b32_e32 v14, 0x8000, v2
	v_mov_b32_e32 v15, v3
	v_lshl_add_u64 v[14:15], v[152:153], 0, v[14:15]
	s_waitcnt lgkmcnt(0)
	global_store_dwordx4 v[14:15], v[148:151], off nt
	ds_read_b128 v[14:17], v9 offset:2176
	s_nop 0
	v_or_b32_e32 v148, 0x10000, v2
	v_mov_b32_e32 v149, v3
	v_lshl_add_u64 v[154:155], v[152:153], 0, v[148:149]
	ds_read_b128 v[148:151], v9 offset:3264
	s_waitcnt lgkmcnt(1)
	global_store_dwordx4 v[154:155], v[14:17], off nt
	s_nop 1
	v_or_b32_e32 v14, 0x18000, v2
	v_mov_b32_e32 v15, v3
	v_lshl_add_u64 v[14:15], v[152:153], 0, v[14:15]
	s_waitcnt lgkmcnt(0)
	global_store_dwordx4 v[14:15], v[148:151], off nt
	ds_read_b128 v[14:17], v9 offset:4352
	s_nop 0
	v_or_b32_e32 v148, 0x20000, v2
	v_mov_b32_e32 v149, v3
	v_lshl_add_u64 v[154:155], v[152:153], 0, v[148:149]
	ds_read_b128 v[148:151], v9 offset:5440
	s_waitcnt lgkmcnt(1)
	global_store_dwordx4 v[154:155], v[14:17], off nt
	s_nop 1
	v_or_b32_e32 v14, 0x28000, v2
	v_mov_b32_e32 v15, v3
	v_lshl_add_u64 v[14:15], v[152:153], 0, v[14:15]
	s_waitcnt lgkmcnt(0)
	global_store_dwordx4 v[14:15], v[148:151], off nt
	ds_read_b128 v[14:17], v9 offset:6528
	s_nop 0
	v_or_b32_e32 v148, 0x30000, v2
	v_mov_b32_e32 v149, v3
	v_lshl_add_u64 v[154:155], v[152:153], 0, v[148:149]
	ds_read_b128 v[148:151], v9 offset:7616
	s_waitcnt lgkmcnt(1)
	global_store_dwordx4 v[154:155], v[14:17], off nt
	s_nop 1
	v_or_b32_e32 v14, 0x38000, v2
	v_mov_b32_e32 v15, v3
	v_lshl_add_u64 v[14:15], v[152:153], 0, v[14:15]
	s_waitcnt lgkmcnt(0)
	global_store_dwordx4 v[14:15], v[148:151], off nt
	ds_read_b128 v[14:17], v9 offset:8704
	s_nop 0
	v_or_b32_e32 v148, 0x40000, v2
	v_mov_b32_e32 v149, v3
	v_lshl_add_u64 v[154:155], v[152:153], 0, v[148:149]
	ds_read_b128 v[148:151], v9 offset:9792
	s_waitcnt lgkmcnt(1)
	global_store_dwordx4 v[154:155], v[14:17], off nt
	s_nop 1
	v_or_b32_e32 v14, 0x48000, v2
	v_mov_b32_e32 v15, v3
	v_lshl_add_u64 v[14:15], v[152:153], 0, v[14:15]
	s_waitcnt lgkmcnt(0)
	global_store_dwordx4 v[14:15], v[148:151], off nt
	ds_read_b128 v[14:17], v9 offset:10880
	s_nop 0
	v_or_b32_e32 v148, 0x50000, v2
	v_mov_b32_e32 v149, v3
	v_lshl_add_u64 v[154:155], v[152:153], 0, v[148:149]
	ds_read_b128 v[148:151], v9 offset:11968
	s_waitcnt lgkmcnt(1)
	global_store_dwordx4 v[154:155], v[14:17], off nt
	s_nop 1
	v_or_b32_e32 v14, 0x58000, v2
	v_mov_b32_e32 v15, v3
	v_lshl_add_u64 v[14:15], v[152:153], 0, v[14:15]
	s_waitcnt lgkmcnt(0)
	global_store_dwordx4 v[14:15], v[148:151], off nt
	ds_read_b128 v[14:17], v9 offset:13056
	s_nop 0
	v_or_b32_e32 v148, 0x60000, v2
	v_mov_b32_e32 v149, v3
	v_lshl_add_u64 v[154:155], v[152:153], 0, v[148:149]
	ds_read_b128 v[148:151], v9 offset:14144
	s_waitcnt lgkmcnt(1)
	global_store_dwordx4 v[154:155], v[14:17], off nt
	v_or_b32_e32 v154, 0x70000, v2
	v_mov_b32_e32 v155, v3
	v_or_b32_e32 v14, 0x68000, v2
	v_mov_b32_e32 v15, v3
	v_lshl_add_u64 v[14:15], v[152:153], 0, v[14:15]
	s_waitcnt lgkmcnt(0)
	global_store_dwordx4 v[14:15], v[148:151], off nt
	ds_read_b128 v[14:17], v9 offset:15232
	ds_read_b128 v[148:151], v9 offset:16320
	v_lshl_add_u64 v[154:155], v[152:153], 0, v[154:155]
	v_or_b32_e32 v2, 0x78000, v2
	s_waitcnt lgkmcnt(1)
	global_store_dwordx4 v[154:155], v[14:17], off nt
	s_nop 1
	v_lshl_add_u64 v[14:15], v[152:153], 0, v[2:3]
	s_waitcnt lgkmcnt(0)
	global_store_dwordx4 v[14:15], v[148:151], off nt

; __device__ __forceinline__ unsigned pk2(float lo, float hi) { f32x2_t v = {lo, hi}; bf16x2_t b = __builtin_convertvector(v, bf16x2_t); return __builtin_bit_cast(unsigned, b); }
;     ...
;           const int pos = tok[tt] & 4095;
;           u16* srow = stg + (tt * 32 + l31) * LD;
; #pragma unroll
;           for (int rq = 0; rq < 4; ++rq) {
;             const int i0 = 8 * rq + 4 * h;
;             const f32x4 c4 = *(const f32x4*)(p.ctab + pos * 32 + i0);
;             const f32x4 s4 = *(const f32x4*)(p.stab + pos * 32 + i0);
;             float y1[4], y2[4];
; #pragma unroll
;             for (int e = 0; e < 4; ++e) {
;               const float x1 = acc[0][tt][rq * 4 + e] * rsv[tt], x2 = acc[1][tt][rq * 4 + e] * rsv[tt];
;               y1[e] = (x1 * c4[e] - x2 * s4[e]) * osc;
;               y2[e] = (x2 * c4[e] + x1 * s4[e]) * osc;
;               ksum[0][rq * 4 + e] += y1[e];
;               ksum[1][rq * 4 + e] += y2[e];
;             }
;             u32x2 w1, w2; w1.x = pk2(y1[0], y1[1]); w1.y = pk2(y1[2], y1[3]); w2.x = pk2(y2[0], y2[1]); w2.y = pk2(y2[2], y2[3]);
;             *(u32x2*)(srow + i0) = w1;
;             *(u32x2*)(srow + 32 + i0) = w2;
;           }
.LBB0_150:
	s_andn2_b64 vcc, exec, s[34:35]
	s_cbranch_vccnz .LBB0_102
	s_cmp_gt_i32 s62, 1
	s_cselect_b64 s[34:35], -1, 0
	s_bfe_u32 s31, s64, 0x30006
	s_and_b64 s[36:37], s[34:35], exec
	s_cselect_b32 s20, s54, 0x98
	s_add_u32 s36, s0, s20
	s_addc_u32 s37, s1, 0
	s_load_dwordx2 s[36:37], s[36:37], 0x0
	s_lshl_b32 s20, s63, 3
	s_or_b32 s38, s31, s20
	s_ashr_i32 s39, s38, 31
	s_ashr_i32 s31, s30, 31
	s_lshl_b64 s[38:39], s[38:39], 19
	s_waitcnt lgkmcnt(0)
	s_add_u32 s36, s36, s38
	s_addc_u32 s37, s37, s39
	s_lshl_b64 s[30:31], s[30:31], 7
	s_add_u32 s30, s36, s30
	s_addc_u32 s31, s37, s31
	v_lshlrev_b32_e32 v148, 7, v12
	v_cndmask_b32_e64 v146, v221, 1.0, s[34:35]
	s_cmp_lt_i32 s62, 2
	v_and_b32_e32 v2, 0x7cf80, v148
	v_mov_b32_e32 v227, v3
	v_lshl_add_u64 v[12:13], s[12:13], 0, v[2:3]
	v_lshl_add_u64 v[16:17], v[12:13], 0, v[226:227]
	global_load_dwordx4 v[12:15], v[16:17], off
	global_load_dwordx4 v[150:153], v[16:17], off offset:32
	global_load_dwordx4 v[154:157], v[16:17], off offset:64
	v_lshl_add_u64 v[162:163], s[10:11], 0, v[2:3]
	global_load_dwordx4 v[158:161], v[16:17], off offset:96
	v_lshl_add_u64 v[16:17], v[162:163], 0, v[226:227]
	global_load_dwordx4 v[162:165], v[16:17], off
	global_load_dwordx4 v[166:169], v[16:17], off offset:32
	global_load_dwordx4 v[170:173], v[16:17], off offset:64
	global_load_dwordx4 v[174:177], v[16:17], off offset:96
	s_waitcnt vmcnt(11)
	v_pk_mul_f32 v[16:17], v[114:115], v[10:11] op_sel_hi:[1,0]
	v_pk_mul_f32 v[114:115], v[130:131], v[10:11] op_sel_hi:[1,0]
	v_pk_mul_f32 v[116:117], v[116:117], v[10:11] op_sel_hi:[1,0]
	v_pk_mul_f32 v[130:131], v[132:133], v[10:11] op_sel_hi:[1,0]
	v_pk_mul_f32 v[118:119], v[118:119], v[10:11] op_sel_hi:[1,0]
	v_pk_mul_f32 v[132:133], v[134:135], v[10:11] op_sel_hi:[1,0]
	v_pk_mul_f32 v[120:121], v[120:121], v[10:11] op_sel_hi:[1,0]
	v_pk_mul_f32 v[134:135], v[136:137], v[10:11] op_sel_hi:[1,0]
	v_pk_mul_f32 v[122:123], v[122:123], v[10:11] op_sel_hi:[1,0]
	v_pk_mul_f32 v[136:137], v[138:139], v[10:11] op_sel_hi:[1,0]
	v_pk_mul_f32 v[124:125], v[124:125], v[10:11] op_sel_hi:[1,0]
	v_pk_mul_f32 v[138:139], v[140:141], v[10:11] op_sel_hi:[1,0]
	v_pk_mul_f32 v[126:127], v[126:127], v[10:11] op_sel_hi:[1,0]
	v_pk_mul_f32 v[140:141], v[142:143], v[10:11] op_sel_hi:[1,0]
	v_pk_mul_f32 v[142:143], v[128:129], v[10:11] op_sel_hi:[1,0]
	v_pk_mul_f32 v[144:145], v[144:145], v[10:11] op_sel_hi:[1,0]
	v_mul_u32_u24_e32 v2, 0x90, v225
	v_add3_u32 v5, s7, v2, v5
	s_waitcnt vmcnt(7)
	v_pk_mul_f32 v[10:11], v[16:17], v[12:13]
	v_pk_mul_f32 v[12:13], v[114:115], v[12:13]
	v_pk_mul_f32 v[128:129], v[116:117], v[14:15]
	v_pk_mul_f32 v[14:15], v[130:131], v[14:15]
	s_waitcnt vmcnt(6)
	v_pk_mul_f32 v[178:179], v[118:119], v[150:151]
	v_pk_mul_f32 v[150:151], v[132:133], v[150:151]
	v_pk_mul_f32 v[180:181], v[120:121], v[152:153]
	v_pk_mul_f32 v[152:153], v[134:135], v[152:153]
	s_waitcnt vmcnt(5)
	v_pk_mul_f32 v[182:183], v[122:123], v[154:155]
	v_pk_mul_f32 v[154:155], v[136:137], v[154:155]
	v_pk_mul_f32 v[184:185], v[124:125], v[156:157]
	s_waitcnt vmcnt(3)
	v_pk_fma_f32 v[10:11], v[114:115], v[162:163], v[10:11]
	v_pk_fma_f32 v[12:13], v[16:17], v[162:163], v[12:13] neg_lo:[0,0,1] neg_hi:[0,0,1]
	v_pk_fma_f32 v[16:17], v[130:131], v[164:165], v[128:129]
	v_pk_fma_f32 v[14:15], v[116:117], v[164:165], v[14:15] neg_lo:[0,0,1] neg_hi:[0,0,1]
	s_waitcnt vmcnt(2)
	v_pk_fma_f32 v[114:115], v[132:133], v[166:167], v[178:179]
	v_pk_fma_f32 v[128:129], v[118:119], v[166:167], v[150:151] neg_lo:[0,0,1] neg_hi:[0,0,1]
	v_pk_fma_f32 v[130:131], v[134:135], v[168:169], v[180:181]
	v_pk_fma_f32 v[150:151], v[120:121], v[168:169], v[152:153] neg_lo:[0,0,1] neg_hi:[0,0,1]
	v_pk_mul_f32 v[156:157], v[138:139], v[156:157]
	v_pk_mul_f32 v[186:187], v[126:127], v[158:159]
	s_waitcnt vmcnt(1)
	v_pk_fma_f32 v[152:153], v[136:137], v[170:171], v[182:183]
	v_pk_fma_f32 v[122:123], v[122:123], v[170:171], v[154:155] neg_lo:[0,0,1] neg_hi:[0,0,1]
	v_pk_fma_f32 v[138:139], v[138:139], v[172:173], v[184:185]
	v_pk_mul_f32 v[120:121], v[146:147], v[10:11] op_sel_hi:[0,1]
	v_pk_mul_f32 v[136:137], v[146:147], v[12:13] op_sel_hi:[0,1]
	v_pk_mul_f32 v[118:119], v[146:147], v[16:17] op_sel_hi:[0,1]
	v_pk_mul_f32 v[134:135], v[146:147], v[14:15] op_sel_hi:[0,1]
	v_pk_mul_f32 v[116:117], v[146:147], v[114:115] op_sel_hi:[0,1]
	v_pk_mul_f32 v[132:133], v[146:147], v[128:129] op_sel_hi:[0,1]
	v_pk_mul_f32 v[114:115], v[146:147], v[130:131] op_sel_hi:[0,1]
	v_pk_mul_f32 v[130:131], v[146:147], v[150:151] op_sel_hi:[0,1]
	v_pk_mul_f32 v[158:159], v[140:141], v[158:159]
	s_waitcnt vmcnt(0)
; __device__ __forceinline__ unsigned pk2(float lo, float hi) { f32x2_t v = {lo, hi}; bf16x2_t b = __builtin_convertvector(v, bf16x2_t); return __builtin_bit_cast(unsigned, b); }
;     ...
;           const int pos = tok[tt] & 4095;
;           u16* srow = stg + (tt * 32 + l31) * LD;
; #pragma unroll
;           for (int rq = 0; rq < 4; ++rq) {
;             const int i0 = 8 * rq + 4 * h;
;             const f32x4 c4 = *(const f32x4*)(p.ctab + pos * 32 + i0);
;             const f32x4 s4 = *(const f32x4*)(p.stab + pos * 32 + i0);
;             float y1[4], y2[4];
; #pragma unroll
;             for (int e = 0; e < 4; ++e) {
;               const float x1 = acc[0][tt][rq * 4 + e] * rsv[tt], x2 = acc[1][tt][rq * 4 + e] * rsv[tt];
;               y1[e] = (x1 * c4[e] - x2 * s4[e]) * osc;
;               y2[e] = (x2 * c4[e] + x1 * s4[e]) * osc;
;               ksum[0][rq * 4 + e] += y1[e];
;               ksum[1][rq * 4 + e] += y2[e];
;             }
;             u32x2 w1, w2; w1.x = pk2(y1[0], y1[1]); w1.y = pk2(y1[2], y1[3]); w2.x = pk2(y2[0], y2[1]); w2.y = pk2(y2[2], y2[3]);
;             *(u32x2*)(srow + i0) = w1;
;             *(u32x2*)(srow + 32 + i0) = w2;
;           }
	v_pk_fma_f32 v[140:141], v[140:141], v[174:175], v[186:187]
	v_pk_mul_f32 v[128:129], v[146:147], v[122:123] op_sel_hi:[0,1]
	v_pk_mul_f32 v[14:15], v[146:147], v[138:139] op_sel_hi:[0,1]
	v_cvt_pk_bf16_f32 v10, v136, v137
	v_cvt_pk_bf16_f32 v11, v134, v135
	v_cvt_pk_bf16_f32 v122, v120, v121
	v_cvt_pk_bf16_f32 v123, v118, v119
	v_cvt_pk_bf16_f32 v138, v132, v133
	v_cvt_pk_bf16_f32 v139, v130, v131
	v_pk_mul_f32 v[12:13], v[146:147], v[140:141] op_sel_hi:[0,1]
	v_cvt_pk_bf16_f32 v140, v116, v117
	v_cvt_pk_bf16_f32 v141, v114, v115
	ds_write2_b64 v5, v[10:11], v[138:139] offset1:2
	ds_write2_b64 v5, v[122:123], v[140:141] offset0:8 offset1:10
	v_pk_mul_f32 v[122:123], v[144:145], v[160:161]
	v_pk_fma_f32 v[124:125], v[124:125], v[172:173], v[156:157] neg_lo:[0,0,1] neg_hi:[0,0,1]
	v_pk_fma_f32 v[154:155], v[126:127], v[174:175], v[158:159] neg_lo:[0,0,1] neg_hi:[0,0,1]
	v_pk_mul_f32 v[10:11], v[142:143], v[160:161]
	v_pk_fma_f32 v[122:123], v[142:143], v[176:177], v[122:123] neg_lo:[0,0,1] neg_hi:[0,0,1]
	v_pk_mul_f32 v[126:127], v[146:147], v[124:125] op_sel_hi:[0,1]
	v_pk_mul_f32 v[124:125], v[146:147], v[154:155] op_sel_hi:[0,1]
	v_pk_fma_f32 v[10:11], v[144:145], v[176:177], v[10:11]
	v_pk_mul_f32 v[122:123], v[146:147], v[122:123] op_sel_hi:[0,1]
	v_pk_mul_f32 v[16:17], v[146:147], v[152:153] op_sel_hi:[0,1]
	v_cvt_pk_bf16_f32 v150, v128, v129
	v_cvt_pk_bf16_f32 v151, v126, v127
	v_pk_mul_f32 v[10:11], v[146:147], v[10:11] op_sel_hi:[0,1]
	v_cvt_pk_bf16_f32 v138, v124, v125
	v_cvt_pk_bf16_f32 v139, v122, v123
	v_cvt_pk_bf16_f32 v152, v16, v17
	v_cvt_pk_bf16_f32 v153, v14, v15
	v_cvt_pk_bf16_f32 v140, v12, v13
	v_cvt_pk_bf16_f32 v141, v10, v11
	ds_write2_b64 v5, v[150:151], v[138:139] offset0:4 offset1:6
	ds_write2_b64 v5, v[152:153], v[140:141] offset0:12 offset1:14
	v_bitop3_b32 v2, v148, s55, v243 bitop3:0xc8
	v_lshl_add_u64 v[138:139], s[12:13], 0, v[2:3]
	v_lshl_add_u64 v[154:155], v[138:139], 0, v[226:227]
	v_lshl_add_u64 v[158:159], s[10:11], 0, v[2:3]
	global_load_dwordx4 v[138:141], v[154:155], off
	global_load_dwordx4 v[142:145], v[154:155], off offset:32
	global_load_dwordx4 v[150:153], v[154:155], off offset:64
	s_nop 0
	global_load_dwordx4 v[154:157], v[154:155], off offset:96
	v_lshl_add_u64 v[170:171], v[158:159], 0, v[226:227]
	global_load_dwordx4 v[158:161], v[170:171], off
	global_load_dwordx4 v[162:165], v[170:171], off offset:32
	global_load_dwordx4 v[166:169], v[170:171], off offset:64
	s_nop 0
	global_load_dwordx4 v[170:173], v[170:171], off offset:96
	v_pk_mul_f32 v[82:83], v[82:83], v[8:9] op_sel_hi:[1,0]
	v_pk_mul_f32 v[98:99], v[98:99], v[8:9] op_sel_hi:[1,0]
	v_pk_mul_f32 v[84:85], v[84:85], v[8:9] op_sel_hi:[1,0]
	v_pk_mul_f32 v[100:101], v[100:101], v[8:9] op_sel_hi:[1,0]
	v_pk_mul_f32 v[86:87], v[86:87], v[8:9] op_sel_hi:[1,0]
	v_pk_mul_f32 v[102:103], v[102:103], v[8:9] op_sel_hi:[1,0]
	v_pk_mul_f32 v[88:89], v[88:89], v[8:9] op_sel_hi:[1,0]
	v_pk_mul_f32 v[104:105], v[104:105], v[8:9] op_sel_hi:[1,0]
	v_pk_mul_f32 v[92:93], v[92:93], v[8:9] op_sel_hi:[1,0]
	v_pk_mul_f32 v[108:109], v[108:109], v[8:9] op_sel_hi:[1,0]
	v_pk_mul_f32 v[94:95], v[94:95], v[8:9] op_sel_hi:[1,0]
	v_pk_mul_f32 v[110:111], v[110:111], v[8:9] op_sel_hi:[1,0]
	v_pk_mul_f32 v[96:97], v[96:97], v[8:9] op_sel_hi:[1,0]
	v_pk_mul_f32 v[90:91], v[90:91], v[8:9] op_sel_hi:[1,0]
	v_pk_mul_f32 v[106:107], v[106:107], v[8:9] op_sel_hi:[1,0]
	v_pk_mul_f32 v[112:113], v[112:113], v[8:9] op_sel_hi:[1,0]
	v_add_u32_e32 v2, 0x1000, v5
	s_waitcnt vmcnt(7)
	v_pk_mul_f32 v[8:9], v[82:83], v[138:139]
	v_pk_mul_f32 v[138:139], v[98:99], v[138:139]
	v_pk_mul_f32 v[174:175], v[84:85], v[140:141]
	v_pk_mul_f32 v[140:141], v[100:101], v[140:141]
	s_waitcnt vmcnt(6)
	v_pk_mul_f32 v[176:177], v[86:87], v[142:143]
	v_pk_mul_f32 v[142:143], v[102:103], v[142:143]
	v_pk_mul_f32 v[178:179], v[88:89], v[144:145]
	v_pk_mul_f32 v[144:145], v[104:105], v[144:145]
	s_waitcnt vmcnt(5)
	v_pk_mul_f32 v[182:183], v[92:93], v[152:153]
	v_pk_mul_f32 v[152:153], v[108:109], v[152:153]
	s_waitcnt vmcnt(4)
	v_pk_mul_f32 v[184:185], v[94:95], v[154:155]
	v_pk_mul_f32 v[154:155], v[110:111], v[154:155]
	v_pk_mul_f32 v[186:187], v[96:97], v[156:157]
	v_pk_mul_f32 v[180:181], v[90:91], v[150:151]
	v_pk_mul_f32 v[150:151], v[106:107], v[150:151]
	s_waitcnt vmcnt(3)
	v_pk_fma_f32 v[8:9], v[98:99], v[158:159], v[8:9]
	v_pk_fma_f32 v[82:83], v[82:83], v[158:159], v[138:139] neg_lo:[0,0,1] neg_hi:[0,0,1]
	v_pk_fma_f32 v[98:99], v[100:101], v[160:161], v[174:175]
	v_pk_fma_f32 v[84:85], v[84:85], v[160:161], v[140:141] neg_lo:[0,0,1] neg_hi:[0,0,1]
	s_waitcnt vmcnt(2)
	v_pk_fma_f32 v[100:101], v[102:103], v[162:163], v[176:177]
	v_pk_fma_f32 v[86:87], v[86:87], v[162:163], v[142:143] neg_lo:[0,0,1] neg_hi:[0,0,1]
	v_pk_fma_f32 v[102:103], v[104:105], v[164:165], v[178:179]
	v_pk_fma_f32 v[104:105], v[88:89], v[164:165], v[144:145] neg_lo:[0,0,1] neg_hi:[0,0,1]
	s_waitcnt vmcnt(1)
	v_pk_fma_f32 v[144:145], v[92:93], v[168:169], v[152:153] neg_lo:[0,0,1] neg_hi:[0,0,1]
	s_waitcnt vmcnt(0)
; __device__ __forceinline__ unsigned pk2(float lo, float hi) { f32x2_t v = {lo, hi}; bf16x2_t b = __builtin_convertvector(v, bf16x2_t); return __builtin_bit_cast(unsigned, b); }
;     ...
;           const int pos = tok[tt] & 4095;
;           u16* srow = stg + (tt * 32 + l31) * LD;
; #pragma unroll
;           for (int rq = 0; rq < 4; ++rq) {
;             const int i0 = 8 * rq + 4 * h;
;             const f32x4 c4 = *(const f32x4*)(p.ctab + pos * 32 + i0);
;             const f32x4 s4 = *(const f32x4*)(p.stab + pos * 32 + i0);
;             float y1[4], y2[4];
; #pragma unroll
;             for (int e = 0; e < 4; ++e) {
;               const float x1 = acc[0][tt][rq * 4 + e] * rsv[tt], x2 = acc[1][tt][rq * 4 + e] * rsv[tt];
;               y1[e] = (x1 * c4[e] - x2 * s4[e]) * osc;
;               y2[e] = (x2 * c4[e] + x1 * s4[e]) * osc;
;               ksum[0][rq * 4 + e] += y1[e];
;               ksum[1][rq * 4 + e] += y2[e];
;             }
;             u32x2 w1, w2; w1.x = pk2(y1[0], y1[1]); w1.y = pk2(y1[2], y1[3]); w2.x = pk2(y2[0], y2[1]); w2.y = pk2(y2[2], y2[3]);
;             *(u32x2*)(srow + i0) = w1;
;             *(u32x2*)(srow + 32 + i0) = w2;
;           }
	v_pk_fma_f32 v[152:153], v[94:95], v[170:171], v[154:155] neg_lo:[0,0,1] neg_hi:[0,0,1]
	v_pk_fma_f32 v[154:155], v[112:113], v[172:173], v[186:187]
	v_pk_mul_f32 v[112:113], v[112:113], v[156:157]
	v_pk_fma_f32 v[138:139], v[106:107], v[166:167], v[180:181]
	v_pk_fma_f32 v[140:141], v[90:91], v[166:167], v[150:151] neg_lo:[0,0,1] neg_hi:[0,0,1]
	v_pk_fma_f32 v[142:143], v[108:109], v[168:169], v[182:183]
	v_pk_fma_f32 v[150:151], v[110:111], v[170:171], v[184:185]
	v_pk_mul_f32 v[110:111], v[146:147], v[82:83] op_sel_hi:[0,1]
	v_pk_mul_f32 v[108:109], v[146:147], v[84:85] op_sel_hi:[0,1]
	v_pk_mul_f32 v[106:107], v[146:147], v[86:87] op_sel_hi:[0,1]
	v_pk_mul_f32 v[104:105], v[146:147], v[104:105] op_sel_hi:[0,1]
	v_pk_fma_f32 v[96:97], v[96:97], v[172:173], v[112:113] neg_lo:[0,0,1] neg_hi:[0,0,1]
	v_pk_mul_f32 v[94:95], v[146:147], v[8:9] op_sel_hi:[0,1]
	v_pk_mul_f32 v[92:93], v[146:147], v[98:99] op_sel_hi:[0,1]
	v_pk_mul_f32 v[90:91], v[146:147], v[100:101] op_sel_hi:[0,1]
	v_pk_mul_f32 v[88:89], v[146:147], v[102:103] op_sel_hi:[0,1]
	v_pk_mul_f32 v[102:103], v[146:147], v[140:141] op_sel_hi:[0,1]
	v_pk_mul_f32 v[100:101], v[146:147], v[144:145] op_sel_hi:[0,1]
	v_pk_mul_f32 v[98:99], v[146:147], v[152:153] op_sel_hi:[0,1]
	v_cvt_pk_bf16_f32 v8, v110, v111
	v_cvt_pk_bf16_f32 v9, v108, v109
	v_cvt_pk_bf16_f32 v140, v106, v107
	v_cvt_pk_bf16_f32 v141, v104, v105
	v_pk_mul_f32 v[96:97], v[146:147], v[96:97] op_sel_hi:[0,1]
	v_pk_mul_f32 v[86:87], v[146:147], v[138:139] op_sel_hi:[0,1]
	v_pk_mul_f32 v[84:85], v[146:147], v[142:143] op_sel_hi:[0,1]
	v_pk_mul_f32 v[82:83], v[146:147], v[150:151] op_sel_hi:[0,1]
	v_cvt_pk_bf16_f32 v138, v94, v95
	v_cvt_pk_bf16_f32 v139, v92, v93
	v_cvt_pk_bf16_f32 v142, v90, v91
	v_cvt_pk_bf16_f32 v143, v88, v89
	v_cvt_pk_bf16_f32 v144, v102, v103
	v_cvt_pk_bf16_f32 v145, v100, v101
	ds_write2_b64 v2, v[8:9], v[140:141] offset0:64 offset1:66
	ds_write2_b64 v2, v[138:139], v[142:143] offset0:72 offset1:74
	v_pk_mul_f32 v[8:9], v[146:147], v[154:155] op_sel_hi:[0,1]
	v_cvt_pk_bf16_f32 v112, v98, v99
	v_cvt_pk_bf16_f32 v113, v96, v97
	v_cvt_pk_bf16_f32 v150, v86, v87
	v_cvt_pk_bf16_f32 v151, v84, v85
	v_cvt_pk_bf16_f32 v138, v82, v83
	v_cvt_pk_bf16_f32 v139, v8, v9
	ds_write2_b64 v2, v[144:145], v[112:113] offset0:68 offset1:70
	ds_write2_b64 v2, v[150:151], v[138:139] offset0:76 offset1:78
	v_bitop3_b32 v2, v148, s56, v244 bitop3:0xc8
	v_lshl_add_u64 v[112:113], s[12:13], 0, v[2:3]
	v_lshl_add_u64 v[112:113], v[112:113], 0, v[226:227]
	global_load_dwordx4 v[138:141], v[112:113], off
	global_load_dwordx4 v[142:145], v[112:113], off offset:32
	global_load_dwordx4 v[150:153], v[112:113], off offset:64
	global_load_dwordx4 v[154:157], v[112:113], off offset:96
	v_lshl_add_u64 v[112:113], s[10:11], 0, v[2:3]
	v_lshl_add_u64 v[112:113], v[112:113], 0, v[226:227]
	global_load_dwordx4 v[158:161], v[112:113], off
	global_load_dwordx4 v[162:165], v[112:113], off offset:32
	global_load_dwordx4 v[166:169], v[112:113], off offset:64
	global_load_dwordx4 v[170:173], v[112:113], off offset:96
	v_pk_mul_f32 v[50:51], v[50:51], v[6:7] op_sel_hi:[1,0]
	v_pk_mul_f32 v[66:67], v[66:67], v[6:7] op_sel_hi:[1,0]
	v_pk_mul_f32 v[52:53], v[52:53], v[6:7] op_sel_hi:[1,0]
	v_pk_mul_f32 v[68:69], v[68:69], v[6:7] op_sel_hi:[1,0]
	v_pk_mul_f32 v[54:55], v[54:55], v[6:7] op_sel_hi:[1,0]
	v_pk_mul_f32 v[70:71], v[70:71], v[6:7] op_sel_hi:[1,0]
	v_pk_mul_f32 v[56:57], v[56:57], v[6:7] op_sel_hi:[1,0]
	v_pk_mul_f32 v[72:73], v[72:73], v[6:7] op_sel_hi:[1,0]
	v_pk_mul_f32 v[60:61], v[60:61], v[6:7] op_sel_hi:[1,0]
	v_pk_mul_f32 v[76:77], v[76:77], v[6:7] op_sel_hi:[1,0]
	v_pk_mul_f32 v[64:65], v[64:65], v[6:7] op_sel_hi:[1,0]
	v_pk_mul_f32 v[58:59], v[58:59], v[6:7] op_sel_hi:[1,0]
	v_pk_mul_f32 v[74:75], v[74:75], v[6:7] op_sel_hi:[1,0]
	v_pk_mul_f32 v[62:63], v[62:63], v[6:7] op_sel_hi:[1,0]
	v_pk_mul_f32 v[78:79], v[78:79], v[6:7] op_sel_hi:[1,0]
	v_pk_mul_f32 v[80:81], v[80:81], v[6:7] op_sel_hi:[1,0]
	v_add_u32_e32 v2, 0x2000, v5
	s_waitcnt vmcnt(7)
	v_pk_mul_f32 v[6:7], v[50:51], v[138:139]
	v_pk_mul_f32 v[112:113], v[66:67], v[138:139]
	v_pk_mul_f32 v[138:139], v[52:53], v[140:141]
	v_pk_mul_f32 v[140:141], v[68:69], v[140:141]
	s_waitcnt vmcnt(6)
	v_pk_mul_f32 v[174:175], v[54:55], v[142:143]
	v_pk_mul_f32 v[142:143], v[70:71], v[142:143]
	v_pk_mul_f32 v[176:177], v[56:57], v[144:145]
	v_pk_mul_f32 v[144:145], v[72:73], v[144:145]
	s_waitcnt vmcnt(5)
	v_pk_mul_f32 v[180:181], v[60:61], v[152:153]
	v_pk_mul_f32 v[152:153], v[76:77], v[152:153]
	s_waitcnt vmcnt(4)
	v_pk_mul_f32 v[184:185], v[64:65], v[156:157]
	v_pk_mul_f32 v[178:179], v[58:59], v[150:151]
	v_pk_mul_f32 v[150:151], v[74:75], v[150:151]
	v_pk_mul_f32 v[182:183], v[62:63], v[154:155]
	v_pk_mul_f32 v[154:155], v[78:79], v[154:155]
	s_waitcnt vmcnt(3)
	v_pk_fma_f32 v[6:7], v[66:67], v[158:159], v[6:7]
	v_pk_fma_f32 v[50:51], v[50:51], v[158:159], v[112:113] neg_lo:[0,0,1] neg_hi:[0,0,1]
	v_pk_fma_f32 v[66:67], v[68:69], v[160:161], v[138:139]
	v_pk_fma_f32 v[52:53], v[52:53], v[160:161], v[140:141] neg_lo:[0,0,1] neg_hi:[0,0,1]
	s_waitcnt vmcnt(2)
	v_pk_fma_f32 v[68:69], v[70:71], v[162:163], v[174:175]
	v_pk_fma_f32 v[54:55], v[54:55], v[162:163], v[142:143] neg_lo:[0,0,1] neg_hi:[0,0,1]
	v_pk_fma_f32 v[70:71], v[72:73], v[164:165], v[176:177]
	v_pk_fma_f32 v[72:73], v[56:57], v[164:165], v[144:145] neg_lo:[0,0,1] neg_hi:[0,0,1]
	s_waitcnt vmcnt(1)
	v_pk_fma_f32 v[142:143], v[60:61], v[168:169], v[152:153] neg_lo:[0,0,1] neg_hi:[0,0,1]
	s_waitcnt vmcnt(0)
; __device__ __forceinline__ unsigned pk2(float lo, float hi) { f32x2_t v = {lo, hi}; bf16x2_t b = __builtin_convertvector(v, bf16x2_t); return __builtin_bit_cast(unsigned, b); }
;     ...
;           const int pos = tok[tt] & 4095;
;           u16* srow = stg + (tt * 32 + l31) * LD;
; #pragma unroll
;           for (int rq = 0; rq < 4; ++rq) {
;             const int i0 = 8 * rq + 4 * h;
;             const f32x4 c4 = *(const f32x4*)(p.ctab + pos * 32 + i0);
;             const f32x4 s4 = *(const f32x4*)(p.stab + pos * 32 + i0);
;             float y1[4], y2[4];
; #pragma unroll
;             for (int e = 0; e < 4; ++e) {
;               const float x1 = acc[0][tt][rq * 4 + e] * rsv[tt], x2 = acc[1][tt][rq * 4 + e] * rsv[tt];
;               y1[e] = (x1 * c4[e] - x2 * s4[e]) * osc;
;               y2[e] = (x2 * c4[e] + x1 * s4[e]) * osc;
;               ksum[0][rq * 4 + e] += y1[e];
;               ksum[1][rq * 4 + e] += y2[e];
;             }
;             u32x2 w1, w2; w1.x = pk2(y1[0], y1[1]); w1.y = pk2(y1[2], y1[3]); w2.x = pk2(y2[0], y2[1]); w2.y = pk2(y2[2], y2[3]);
;             *(u32x2*)(srow + i0) = w1;
;             *(u32x2*)(srow + 32 + i0) = w2;
;           }
	v_pk_fma_f32 v[152:153], v[80:81], v[172:173], v[184:185]
	v_pk_mul_f32 v[80:81], v[80:81], v[156:157]
	v_pk_fma_f32 v[112:113], v[74:75], v[166:167], v[178:179]
	v_pk_fma_f32 v[138:139], v[58:59], v[166:167], v[150:151] neg_lo:[0,0,1] neg_hi:[0,0,1]
	v_pk_fma_f32 v[140:141], v[76:77], v[168:169], v[180:181]
	v_pk_fma_f32 v[144:145], v[78:79], v[170:171], v[182:183]
	v_pk_fma_f32 v[150:151], v[62:63], v[170:171], v[154:155] neg_lo:[0,0,1] neg_hi:[0,0,1]
	v_pk_mul_f32 v[78:79], v[146:147], v[50:51] op_sel_hi:[0,1]
	v_pk_mul_f32 v[76:77], v[146:147], v[52:53] op_sel_hi:[0,1]
	v_pk_mul_f32 v[74:75], v[146:147], v[54:55] op_sel_hi:[0,1]
	v_pk_mul_f32 v[72:73], v[146:147], v[72:73] op_sel_hi:[0,1]
	v_pk_fma_f32 v[64:65], v[64:65], v[172:173], v[80:81] neg_lo:[0,0,1] neg_hi:[0,0,1]
	v_pk_mul_f32 v[62:63], v[146:147], v[6:7] op_sel_hi:[0,1]
	v_pk_mul_f32 v[60:61], v[146:147], v[66:67] op_sel_hi:[0,1]
	v_pk_mul_f32 v[58:59], v[146:147], v[68:69] op_sel_hi:[0,1]
	v_pk_mul_f32 v[56:57], v[146:147], v[70:71] op_sel_hi:[0,1]
	v_pk_mul_f32 v[70:71], v[146:147], v[138:139] op_sel_hi:[0,1]
	v_pk_mul_f32 v[68:69], v[146:147], v[142:143] op_sel_hi:[0,1]
	v_pk_mul_f32 v[66:67], v[146:147], v[150:151] op_sel_hi:[0,1]
	v_cvt_pk_bf16_f32 v6, v78, v79
	v_cvt_pk_bf16_f32 v7, v76, v77
	v_cvt_pk_bf16_f32 v138, v74, v75
	v_cvt_pk_bf16_f32 v139, v72, v73
	v_pk_mul_f32 v[64:65], v[146:147], v[64:65] op_sel_hi:[0,1]
	v_pk_mul_f32 v[54:55], v[146:147], v[112:113] op_sel_hi:[0,1]
	v_pk_mul_f32 v[52:53], v[146:147], v[140:141] op_sel_hi:[0,1]
	v_pk_mul_f32 v[50:51], v[146:147], v[144:145] op_sel_hi:[0,1]
	v_cvt_pk_bf16_f32 v112, v62, v63
	v_cvt_pk_bf16_f32 v113, v60, v61
	v_cvt_pk_bf16_f32 v140, v58, v59
	v_cvt_pk_bf16_f32 v141, v56, v57
	v_cvt_pk_bf16_f32 v142, v70, v71
	v_cvt_pk_bf16_f32 v143, v68, v69
	ds_write2_b64 v2, v[6:7], v[138:139] offset0:128 offset1:130
	ds_write2_b64 v2, v[112:113], v[140:141] offset0:136 offset1:138
	v_pk_mul_f32 v[6:7], v[146:147], v[152:153] op_sel_hi:[0,1]
	v_cvt_pk_bf16_f32 v80, v66, v67
	v_cvt_pk_bf16_f32 v81, v64, v65
	v_cvt_pk_bf16_f32 v144, v54, v55
	v_cvt_pk_bf16_f32 v145, v52, v53
	v_cvt_pk_bf16_f32 v112, v50, v51
	v_cvt_pk_bf16_f32 v113, v6, v7
	ds_write2_b64 v2, v[142:143], v[80:81] offset0:132 offset1:134
	ds_write2_b64 v2, v[144:145], v[112:113] offset0:140 offset1:142
	v_bitop3_b32 v2, v148, s57, v245 bitop3:0xc8
	v_lshl_add_u64 v[80:81], s[12:13], 0, v[2:3]
	v_lshl_add_u64 v[80:81], v[80:81], 0, v[226:227]
	global_load_dwordx4 v[138:141], v[80:81], off
	global_load_dwordx4 v[142:145], v[80:81], off offset:32
	global_load_dwordx4 v[148:151], v[80:81], off offset:64
	global_load_dwordx4 v[152:155], v[80:81], off offset:96
	v_lshl_add_u64 v[80:81], s[10:11], 0, v[2:3]
	v_lshl_add_u64 v[80:81], v[80:81], 0, v[226:227]
	global_load_dwordx4 v[156:159], v[80:81], off
	global_load_dwordx4 v[160:163], v[80:81], off offset:32
	global_load_dwordx4 v[164:167], v[80:81], off offset:64
	global_load_dwordx4 v[168:171], v[80:81], off offset:96
	v_pk_mul_f32 v[18:19], v[18:19], v[4:5] op_sel_hi:[1,0]
	v_pk_mul_f32 v[34:35], v[34:35], v[4:5] op_sel_hi:[1,0]
	v_pk_mul_f32 v[20:21], v[20:21], v[4:5] op_sel_hi:[1,0]
	v_pk_mul_f32 v[36:37], v[36:37], v[4:5] op_sel_hi:[1,0]
	v_pk_mul_f32 v[22:23], v[22:23], v[4:5] op_sel_hi:[1,0]
	v_pk_mul_f32 v[38:39], v[38:39], v[4:5] op_sel_hi:[1,0]
	v_pk_mul_f32 v[24:25], v[24:25], v[4:5] op_sel_hi:[1,0]
	v_pk_mul_f32 v[40:41], v[40:41], v[4:5] op_sel_hi:[1,0]
	v_pk_mul_f32 v[26:27], v[26:27], v[4:5] op_sel_hi:[1,0]
	v_pk_mul_f32 v[42:43], v[42:43], v[4:5] op_sel_hi:[1,0]
	v_pk_mul_f32 v[32:33], v[32:33], v[4:5] op_sel_hi:[1,0]
	v_add_u32_e32 v2, 0x3000, v5
	v_pk_mul_f32 v[28:29], v[28:29], v[4:5] op_sel_hi:[1,0]
	v_pk_mul_f32 v[44:45], v[44:45], v[4:5] op_sel_hi:[1,0]
	v_pk_mul_f32 v[30:31], v[30:31], v[4:5] op_sel_hi:[1,0]
	v_pk_mul_f32 v[46:47], v[46:47], v[4:5] op_sel_hi:[1,0]
	v_pk_mul_f32 v[48:49], v[48:49], v[4:5] op_sel_hi:[1,0]
	s_waitcnt vmcnt(7)
	v_pk_mul_f32 v[4:5], v[18:19], v[138:139]
	v_pk_mul_f32 v[80:81], v[34:35], v[138:139]
	v_pk_mul_f32 v[112:113], v[20:21], v[140:141]
	v_pk_mul_f32 v[138:139], v[36:37], v[140:141]
	s_waitcnt vmcnt(6)
	v_pk_mul_f32 v[140:141], v[22:23], v[142:143]
	v_pk_mul_f32 v[142:143], v[38:39], v[142:143]
	v_pk_mul_f32 v[172:173], v[24:25], v[144:145]
	v_pk_mul_f32 v[144:145], v[40:41], v[144:145]
	s_waitcnt vmcnt(5)
	v_pk_mul_f32 v[174:175], v[26:27], v[148:149]
	v_pk_mul_f32 v[148:149], v[42:43], v[148:149]
	s_waitcnt vmcnt(4)
	v_pk_mul_f32 v[180:181], v[32:33], v[154:155]
	v_pk_mul_f32 v[176:177], v[28:29], v[150:151]
	v_pk_mul_f32 v[150:151], v[44:45], v[150:151]
	v_pk_mul_f32 v[178:179], v[30:31], v[152:153]
	v_pk_mul_f32 v[152:153], v[46:47], v[152:153]
	s_waitcnt vmcnt(3)
	v_pk_fma_f32 v[4:5], v[34:35], v[156:157], v[4:5]
	v_pk_fma_f32 v[18:19], v[18:19], v[156:157], v[80:81] neg_lo:[0,0,1] neg_hi:[0,0,1]
	v_pk_fma_f32 v[34:35], v[36:37], v[158:159], v[112:113]
	v_pk_fma_f32 v[20:21], v[20:21], v[158:159], v[138:139] neg_lo:[0,0,1] neg_hi:[0,0,1]
	s_waitcnt vmcnt(2)
	v_pk_fma_f32 v[36:37], v[38:39], v[160:161], v[140:141]
	v_pk_fma_f32 v[22:23], v[22:23], v[160:161], v[142:143] neg_lo:[0,0,1] neg_hi:[0,0,1]
	v_pk_fma_f32 v[38:39], v[40:41], v[162:163], v[172:173]
	v_pk_fma_f32 v[40:41], v[24:25], v[162:163], v[144:145] neg_lo:[0,0,1] neg_hi:[0,0,1]
	s_waitcnt vmcnt(1)
	v_pk_fma_f32 v[112:113], v[26:27], v[164:165], v[148:149] neg_lo:[0,0,1] neg_hi:[0,0,1]
	s_waitcnt vmcnt(0)
; __device__ __forceinline__ unsigned pk2(float lo, float hi) { f32x2_t v = {lo, hi}; bf16x2_t b = __builtin_convertvector(v, bf16x2_t); return __builtin_bit_cast(unsigned, b); }
;     ...
;       auto flush_rows = [&](u16* gbase, size_t ldd) {
; #pragma unroll
;         for (int it = 0; it < 16; ++it) {
;           const int r = it * 8 + (lane >> 3), ch = lane & 7;
;           *(u32x4*)(gbase + (size_t)r * ldd + ch * 8) = *(const u32x4*)(stg + r * LD + ch * 8);
;         }
;     ...
;             u32x2 w1, w2; w1.x = pk2(y1[0], y1[1]); w1.y = pk2(y1[2], y1[3]); w2.x = pk2(y2[0], y2[1]); w2.y = pk2(y2[2], y2[3]);
;             *(u32x2*)(srow + i0) = w1;
;             *(u32x2*)(srow + 32 + i0) = w2;
;           }
;         }
;         flush_rows(dst + ((size_t)(bq * 8 + head) * SEQ + pos0) * 64, 64);
	v_pk_fma_f32 v[148:149], v[48:49], v[170:171], v[180:181]
	v_pk_mul_f32 v[48:49], v[48:49], v[154:155]
	v_pk_fma_f32 v[80:81], v[42:43], v[164:165], v[174:175]
	v_pk_fma_f32 v[138:139], v[44:45], v[166:167], v[176:177]
	v_pk_fma_f32 v[140:141], v[28:29], v[166:167], v[150:151] neg_lo:[0,0,1] neg_hi:[0,0,1]
	v_pk_fma_f32 v[142:143], v[46:47], v[168:169], v[178:179]
	v_pk_fma_f32 v[144:145], v[30:31], v[168:169], v[152:153] neg_lo:[0,0,1] neg_hi:[0,0,1]
	v_pk_mul_f32 v[46:47], v[146:147], v[18:19] op_sel_hi:[0,1]
	v_pk_mul_f32 v[44:45], v[146:147], v[20:21] op_sel_hi:[0,1]
	v_pk_mul_f32 v[42:43], v[146:147], v[22:23] op_sel_hi:[0,1]
	v_pk_mul_f32 v[40:41], v[146:147], v[40:41] op_sel_hi:[0,1]
	v_pk_fma_f32 v[32:33], v[32:33], v[170:171], v[48:49] neg_lo:[0,0,1] neg_hi:[0,0,1]
	v_pk_mul_f32 v[30:31], v[146:147], v[4:5] op_sel_hi:[0,1]
	v_pk_mul_f32 v[28:29], v[146:147], v[34:35] op_sel_hi:[0,1]
	v_pk_mul_f32 v[26:27], v[146:147], v[36:37] op_sel_hi:[0,1]
	v_pk_mul_f32 v[24:25], v[146:147], v[38:39] op_sel_hi:[0,1]
	v_pk_mul_f32 v[38:39], v[146:147], v[112:113] op_sel_hi:[0,1]
	v_pk_mul_f32 v[36:37], v[146:147], v[140:141] op_sel_hi:[0,1]
	v_pk_mul_f32 v[34:35], v[146:147], v[144:145] op_sel_hi:[0,1]
	v_cvt_pk_bf16_f32 v4, v46, v47
	v_cvt_pk_bf16_f32 v5, v44, v45
	v_cvt_pk_bf16_f32 v112, v42, v43
	v_cvt_pk_bf16_f32 v113, v40, v41
	v_pk_mul_f32 v[32:33], v[146:147], v[32:33] op_sel_hi:[0,1]
	v_pk_mul_f32 v[22:23], v[146:147], v[80:81] op_sel_hi:[0,1]
	v_pk_mul_f32 v[20:21], v[146:147], v[138:139] op_sel_hi:[0,1]
	v_pk_mul_f32 v[18:19], v[146:147], v[142:143] op_sel_hi:[0,1]
	v_cvt_pk_bf16_f32 v80, v30, v31
	v_cvt_pk_bf16_f32 v81, v28, v29
	v_cvt_pk_bf16_f32 v138, v26, v27
	v_cvt_pk_bf16_f32 v139, v24, v25
	v_cvt_pk_bf16_f32 v140, v38, v39
	v_cvt_pk_bf16_f32 v141, v36, v37
	ds_write2_b64 v2, v[4:5], v[112:113] offset0:192 offset1:194
	ds_write2_b64 v2, v[80:81], v[138:139] offset0:200 offset1:202
	v_pk_mul_f32 v[4:5], v[146:147], v[148:149] op_sel_hi:[0,1]
	v_cvt_pk_bf16_f32 v48, v34, v35
	v_cvt_pk_bf16_f32 v49, v32, v33
	v_cvt_pk_bf16_f32 v142, v22, v23
	v_cvt_pk_bf16_f32 v143, v20, v21
	v_cvt_pk_bf16_f32 v80, v18, v19
	v_cvt_pk_bf16_f32 v81, v4, v5
	ds_write2_b64 v2, v[140:141], v[48:49] offset0:196 offset1:198
	ds_write2_b64 v2, v[142:143], v[80:81] offset0:204 offset1:206
	v_lshrrev_b32_e32 v2, 3, v147
	v_lshlrev_b32_e32 v48, 4, v225
	v_mul_u32_u24_e32 v49, 0x90, v2
	v_and_b32_e32 v48, 0x70, v48
	v_add3_u32 v112, s7, v49, v48
	ds_read_b128 v[138:141], v112
	ds_read_b128 v[142:145], v112 offset:1152
	v_lshlrev_b32_e32 v2, 7, v2
	v_lshl_add_u64 v[80:81], s[30:31], 0, v[2:3]
	v_mov_b32_e32 v49, v3
	v_lshl_add_u64 v[80:81], v[80:81], 0, v[48:49]
	s_waitcnt lgkmcnt(1)
	global_store_dwordx4 v[80:81], v[138:141], off nt
	v_or_b32_e32 v80, 0x400, v2
	v_mov_b32_e32 v81, v3
	v_lshl_add_u64 v[80:81], s[30:31], 0, v[80:81]
	ds_read_b128 v[138:141], v112 offset:2304
	v_lshl_add_u64 v[80:81], v[80:81], 0, v[48:49]
	s_waitcnt lgkmcnt(1)
	global_store_dwordx4 v[80:81], v[142:145], off nt
	v_or_b32_e32 v80, 0x800, v2
	v_mov_b32_e32 v81, v3
	v_lshl_add_u64 v[80:81], s[30:31], 0, v[80:81]
	ds_read_b128 v[142:145], v112 offset:3456
	v_lshl_add_u64 v[80:81], v[80:81], 0, v[48:49]
	s_waitcnt lgkmcnt(1)
	global_store_dwordx4 v[80:81], v[138:141], off nt
	v_or_b32_e32 v80, 0xc00, v2
	v_mov_b32_e32 v81, v3
	v_lshl_add_u64 v[80:81], s[30:31], 0, v[80:81]
	ds_read_b128 v[138:141], v112 offset:4608
	v_lshl_add_u64 v[80:81], v[80:81], 0, v[48:49]
	s_waitcnt lgkmcnt(1)
	global_store_dwordx4 v[80:81], v[142:145], off nt
	v_or_b32_e32 v80, 0x1000, v2
	v_mov_b32_e32 v81, v3
	v_lshl_add_u64 v[80:81], s[30:31], 0, v[80:81]
	ds_read_b128 v[142:145], v112 offset:5760
	v_lshl_add_u64 v[80:81], v[80:81], 0, v[48:49]
	s_waitcnt lgkmcnt(1)
	global_store_dwordx4 v[80:81], v[138:141], off nt
	v_or_b32_e32 v80, 0x1400, v2
	v_mov_b32_e32 v81, v3
	v_lshl_add_u64 v[80:81], s[30:31], 0, v[80:81]
	ds_read_b128 v[138:141], v112 offset:6912
	v_lshl_add_u64 v[80:81], v[80:81], 0, v[48:49]
	s_waitcnt lgkmcnt(1)
	global_store_dwordx4 v[80:81], v[142:145], off nt
	v_or_b32_e32 v80, 0x1800, v2
	v_mov_b32_e32 v81, v3
	v_lshl_add_u64 v[80:81], s[30:31], 0, v[80:81]
	ds_read_b128 v[142:145], v112 offset:8064
	v_lshl_add_u64 v[80:81], v[80:81], 0, v[48:49]
	s_waitcnt lgkmcnt(1)
	global_store_dwordx4 v[80:81], v[138:141], off nt
	v_or_b32_e32 v80, 0x1c00, v2
	v_mov_b32_e32 v81, v3
	v_lshl_add_u64 v[80:81], s[30:31], 0, v[80:81]
	ds_read_b128 v[138:141], v112 offset:9216
	v_lshl_add_u64 v[80:81], v[80:81], 0, v[48:49]
	s_waitcnt lgkmcnt(1)
	global_store_dwordx4 v[80:81], v[142:145], off nt
	v_or_b32_e32 v80, 0x2000, v2
	v_mov_b32_e32 v81, v3
	v_lshl_add_u64 v[80:81], s[30:31], 0, v[80:81]
	ds_read_b128 v[142:145], v112 offset:10368
	v_lshl_add_u64 v[80:81], v[80:81], 0, v[48:49]
	s_waitcnt lgkmcnt(1)
	global_store_dwordx4 v[80:81], v[138:141], off nt
	v_or_b32_e32 v80, 0x2400, v2
	v_mov_b32_e32 v81, v3
	v_lshl_add_u64 v[80:81], s[30:31], 0, v[80:81]
	ds_read_b128 v[138:141], v112 offset:11520
	v_lshl_add_u64 v[80:81], v[80:81], 0, v[48:49]
	s_waitcnt lgkmcnt(1)
	global_store_dwordx4 v[80:81], v[142:145], off nt
	v_or_b32_e32 v80, 0x2800, v2
	v_mov_b32_e32 v81, v3
	v_lshl_add_u64 v[80:81], s[30:31], 0, v[80:81]
	ds_read_b128 v[142:145], v112 offset:12672
	v_lshl_add_u64 v[80:81], v[80:81], 0, v[48:49]
	s_waitcnt lgkmcnt(1)
	global_store_dwordx4 v[80:81], v[138:141], off nt
	v_or_b32_e32 v80, 0x2c00, v2
	v_mov_b32_e32 v81, v3
	v_lshl_add_u64 v[80:81], s[30:31], 0, v[80:81]
	ds_read_b128 v[138:141], v112 offset:13824
	v_lshl_add_u64 v[80:81], v[80:81], 0, v[48:49]
	s_waitcnt lgkmcnt(1)
	global_store_dwordx4 v[80:81], v[142:145], off nt
	v_or_b32_e32 v80, 0x3000, v2
	v_mov_b32_e32 v81, v3
	v_lshl_add_u64 v[80:81], s[30:31], 0, v[80:81]
	ds_read_b128 v[142:145], v112 offset:14976
	v_lshl_add_u64 v[80:81], v[80:81], 0, v[48:49]
	s_waitcnt lgkmcnt(1)
	global_store_dwordx4 v[80:81], v[138:141], off nt
	v_or_b32_e32 v80, 0x3400, v2
	v_mov_b32_e32 v81, v3
	v_lshl_add_u64 v[80:81], s[30:31], 0, v[80:81]
	ds_read_b128 v[138:141], v112 offset:16128
	v_lshl_add_u64 v[80:81], v[80:81], 0, v[48:49]
	s_waitcnt lgkmcnt(1)
	global_store_dwordx4 v[80:81], v[142:145], off nt
	v_or_b32_e32 v80, 0x3800, v2
	v_mov_b32_e32 v81, v3
	ds_read_b128 v[142:145], v112 offset:17280
	v_lshl_add_u64 v[80:81], s[30:31], 0, v[80:81]
	v_lshl_add_u64 v[80:81], v[80:81], 0, v[48:49]
	v_or_b32_e32 v2, 0x3c00, v2
	s_waitcnt lgkmcnt(1)
	global_store_dwordx4 v[80:81], v[138:141], off nt
	v_lshl_add_u64 v[80:81], s[30:31], 0, v[2:3]
	v_lshl_add_u64 v[48:49], v[80:81], 0, v[48:49]
	s_waitcnt lgkmcnt(0)
	global_store_dwordx4 v[48:49], v[142:145], off nt
	s_cbranch_scc1 .LBB0_217
; __device__ __forceinline__ int rm32(int reg, int h) { return (reg & 3) + 8 * (reg >> 2) + 4 * h; }
;     ...
;         if (!isq) {
; #pragma unroll
;           for (int ct = 0; ct < 2; ++ct)
; #pragma unroll
;             for (int r = 0; r < 16; ++r) {
;               float v = ksum[ct][r];
;               v += __shfl_xor(v, 1); v += __shfl_xor(v, 2); v += __shfl_xor(v, 4); v += __shfl_xor(v, 8); v += __shfl_xor(v, 16);
;               if (l31 == 0) red[wr * 256 + wc * 64 + ct * 32 + rm32(r, h)] = v;
;             }
	v_add_f32_e32 v2, 0, v136
	v_add_f32_e32 v2, v2, v110
	v_add_f32_e32 v2, v2, v78
	v_add_f32_e32 v48, v2, v46
	v_and_b32_e32 v46, 64, v246
	v_xor_b32_e32 v2, 1, v246
	v_add_u32_e32 v78, 64, v46
	v_cmp_lt_i32_e32 vcc, v2, v78
	v_xor_b32_e32 v46, 2, v246
	v_xor_b32_e32 v112, 16, v246
	v_cndmask_b32_e32 v2, v246, v2, vcc
	v_lshlrev_b32_e32 v2, 2, v2
	ds_bpermute_b32 v49, v2, v48
	v_cmp_lt_i32_e32 vcc, v46, v78
	s_and_b32 s7, s60, 0xffffff00
	v_lshlrev_b32_e32 v80, 2, v247
	v_cndmask_b32_e32 v46, v246, v46, vcc
	v_lshlrev_b32_e32 v46, 2, v46
	s_waitcnt lgkmcnt(0)
	v_add_f32_e32 v49, v48, v49
	ds_bpermute_b32 v81, v46, v49
	v_xor_b32_e32 v48, 4, v246
	v_cmp_lt_i32_e32 vcc, v48, v78
	s_add_i32 s61, s61, s7
	v_or_b32_e32 v80, s61, v80
	v_cndmask_b32_e32 v48, v246, v48, vcc
	v_lshlrev_b32_e32 v48, 2, v48
	s_waitcnt lgkmcnt(0)
	v_add_f32_e32 v81, v49, v81
	ds_bpermute_b32 v110, v48, v81
	v_xor_b32_e32 v49, 8, v246
	v_cmp_lt_i32_e32 vcc, v49, v78
	s_waitcnt lgkmcnt(0)
	v_add_f32_e32 v81, v81, v110
	v_cndmask_b32_e32 v49, v246, v49, vcc
	v_lshlrev_b32_e32 v49, 2, v49
	ds_bpermute_b32 v110, v49, v81
	v_cmp_lt_i32_e32 vcc, v112, v78
	s_waitcnt lgkmcnt(0)
	v_add_f32_e32 v81, v81, v110
	v_cndmask_b32_e32 v78, v246, v112, vcc
	v_lshlrev_b32_e32 v78, 2, v78
	ds_bpermute_b32 v110, v78, v81
	v_cmp_eq_u32_e32 vcc, 0, v225
	s_and_saveexec_b64 s[30:31], vcc
	s_cbranch_execz .LBB0_154
	v_lshl_add_u32 v112, v80, 2, 0
	v_add_u32_e32 v112, 0x24000, v112
	s_waitcnt lgkmcnt(0)
	v_add_f32_e32 v81, v81, v110
	ds_write_b32 v112, v81

; __device__ __forceinline__ unsigned pk2(float lo, float hi) { f32x2_t v = {lo, hi}; bf16x2_t b = __builtin_convertvector(v, bf16x2_t); return __builtin_bit_cast(unsigned, b); }
; __device__ __forceinline__ float fsigmoid(float x) { return __builtin_amdgcn_rcpf(1.f + fexp(-x)); }
;     ...
; #pragma unroll
;         for (int tt = 0; tt < 4; ++tt) {
;           u16* srow = stg + (tt * 32 + l31) * LD;
; #pragma unroll
;           for (int ct = 0; ct < 2; ++ct)
; #pragma unroll
;             for (int rq = 0; rq < 4; ++rq) {
;               float v[4];
; #pragma unroll
;               for (int e = 0; e < 4; ++e) { v[e] = acc[ct][tt][rq * 4 + e] * rsv[tt]; if (act) v[e] = v[e] * fsigmoid(v[e]); }
;               u32x2 w; w.x = pk2(v[0], v[1]); w.y = pk2(v[2], v[3]);
;               *(u32x2*)(srow + ct * 32 + 8 * rq + 4 * h) = w;
;             }
.Lp1_raw:
	s_add_u32 s38, s0, s38
	s_addc_u32 s39, s1, s39
	s_load_dwordx2 s[38:39], s[38:39], 0x0
	s_add_i32 s20, s35, s64
	v_mul_u32_u24_e32 v2, 0x90, v225
	v_add3_u32 v2, s7, v5, v2
	s_waitcnt vmcnt(3)
	v_pk_mul_f32 v[178:179], v[114:115], v[10:11] op_sel_hi:[1,0]
	v_pk_mul_f32 v[180:181], v[116:117], v[10:11] op_sel_hi:[1,0]
	v_cvt_pk_bf16_f32 v194, v178, v179
	v_cvt_pk_bf16_f32 v195, v180, v181
	ds_write_b64 v2, v[194:195] offset:0
	v_pk_mul_f32 v[182:183], v[118:119], v[10:11] op_sel_hi:[1,0]
	v_pk_mul_f32 v[184:185], v[120:121], v[10:11] op_sel_hi:[1,0]
	v_cvt_pk_bf16_f32 v196, v182, v183
	v_cvt_pk_bf16_f32 v197, v184, v185
	ds_write_b64 v2, v[196:197] offset:16
	v_pk_mul_f32 v[186:187], v[122:123], v[10:11] op_sel_hi:[1,0]
	v_pk_mul_f32 v[188:189], v[124:125], v[10:11] op_sel_hi:[1,0]
	v_cvt_pk_bf16_f32 v198, v186, v187
	v_cvt_pk_bf16_f32 v199, v188, v189
	ds_write_b64 v2, v[198:199] offset:32
	v_pk_mul_f32 v[190:191], v[126:127], v[10:11] op_sel_hi:[1,0]
	v_pk_mul_f32 v[192:193], v[128:129], v[10:11] op_sel_hi:[1,0]
	v_cvt_pk_bf16_f32 v200, v190, v191
	v_cvt_pk_bf16_f32 v201, v192, v193
	ds_write_b64 v2, v[200:201] offset:48
	v_pk_mul_f32 v[178:179], v[130:131], v[10:11] op_sel_hi:[1,0]
	v_pk_mul_f32 v[180:181], v[132:133], v[10:11] op_sel_hi:[1,0]
	v_cvt_pk_bf16_f32 v202, v178, v179
	v_cvt_pk_bf16_f32 v203, v180, v181
	ds_write_b64 v2, v[202:203] offset:64
	v_pk_mul_f32 v[182:183], v[134:135], v[10:11] op_sel_hi:[1,0]
	v_pk_mul_f32 v[184:185], v[136:137], v[10:11] op_sel_hi:[1,0]
	v_cvt_pk_bf16_f32 v204, v182, v183
	v_cvt_pk_bf16_f32 v205, v184, v185
	ds_write_b64 v2, v[204:205] offset:80
	v_pk_mul_f32 v[186:187], v[138:139], v[10:11] op_sel_hi:[1,0]
	v_pk_mul_f32 v[188:189], v[140:141], v[10:11] op_sel_hi:[1,0]
	v_cvt_pk_bf16_f32 v206, v186, v187
	v_cvt_pk_bf16_f32 v207, v188, v189
	ds_write_b64 v2, v[206:207] offset:96
	v_pk_mul_f32 v[190:191], v[142:143], v[10:11] op_sel_hi:[1,0]
	v_pk_mul_f32 v[192:193], v[144:145], v[10:11] op_sel_hi:[1,0]
	v_cvt_pk_bf16_f32 v208, v190, v191
	v_cvt_pk_bf16_f32 v209, v192, v193
	ds_write_b64 v2, v[208:209] offset:112
	s_waitcnt vmcnt(2)
	v_pk_mul_f32 v[178:179], v[82:83], v[8:9] op_sel_hi:[1,0]
	v_pk_mul_f32 v[180:181], v[84:85], v[8:9] op_sel_hi:[1,0]
	v_cvt_pk_bf16_f32 v194, v178, v179
	v_cvt_pk_bf16_f32 v195, v180, v181
	ds_write_b64 v2, v[194:195] offset:4608
	v_pk_mul_f32 v[182:183], v[86:87], v[8:9] op_sel_hi:[1,0]
	v_pk_mul_f32 v[184:185], v[88:89], v[8:9] op_sel_hi:[1,0]
	v_cvt_pk_bf16_f32 v196, v182, v183
	v_cvt_pk_bf16_f32 v197, v184, v185
	ds_write_b64 v2, v[196:197] offset:4624
	v_pk_mul_f32 v[186:187], v[90:91], v[8:9] op_sel_hi:[1,0]
	v_pk_mul_f32 v[188:189], v[92:93], v[8:9] op_sel_hi:[1,0]
	v_cvt_pk_bf16_f32 v198, v186, v187
	v_cvt_pk_bf16_f32 v199, v188, v189
	ds_write_b64 v2, v[198:199] offset:4640
	v_pk_mul_f32 v[190:191], v[94:95], v[8:9] op_sel_hi:[1,0]
	v_pk_mul_f32 v[192:193], v[96:97], v[8:9] op_sel_hi:[1,0]
	v_cvt_pk_bf16_f32 v200, v190, v191
	v_cvt_pk_bf16_f32 v201, v192, v193
	ds_write_b64 v2, v[200:201] offset:4656
	v_pk_mul_f32 v[178:179], v[98:99], v[8:9] op_sel_hi:[1,0]
	v_pk_mul_f32 v[180:181], v[100:101], v[8:9] op_sel_hi:[1,0]
	v_cvt_pk_bf16_f32 v202, v178, v179
	v_cvt_pk_bf16_f32 v203, v180, v181
	ds_write_b64 v2, v[202:203] offset:4672
	v_pk_mul_f32 v[182:183], v[102:103], v[8:9] op_sel_hi:[1,0]
	v_pk_mul_f32 v[184:185], v[104:105], v[8:9] op_sel_hi:[1,0]
	v_cvt_pk_bf16_f32 v204, v182, v183
	v_cvt_pk_bf16_f32 v205, v184, v185
	ds_write_b64 v2, v[204:205] offset:4688
	v_pk_mul_f32 v[186:187], v[106:107], v[8:9] op_sel_hi:[1,0]
	v_pk_mul_f32 v[188:189], v[108:109], v[8:9] op_sel_hi:[1,0]
	v_cvt_pk_bf16_f32 v206, v186, v187
	v_cvt_pk_bf16_f32 v207, v188, v189
	ds_write_b64 v2, v[206:207] offset:4704
	v_pk_mul_f32 v[190:191], v[110:111], v[8:9] op_sel_hi:[1,0]
	v_pk_mul_f32 v[192:193], v[112:113], v[8:9] op_sel_hi:[1,0]
	v_cvt_pk_bf16_f32 v208, v190, v191
	v_cvt_pk_bf16_f32 v209, v192, v193
	ds_write_b64 v2, v[208:209] offset:4720
	s_waitcnt vmcnt(1)
	v_pk_mul_f32 v[178:179], v[50:51], v[6:7] op_sel_hi:[1,0]
	v_pk_mul_f32 v[180:181], v[52:53], v[6:7] op_sel_hi:[1,0]
	v_cvt_pk_bf16_f32 v194, v178, v179
	v_cvt_pk_bf16_f32 v195, v180, v181
	ds_write_b64 v2, v[194:195] offset:9216
	v_pk_mul_f32 v[182:183], v[54:55], v[6:7] op_sel_hi:[1,0]
	v_pk_mul_f32 v[184:185], v[56:57], v[6:7] op_sel_hi:[1,0]
	v_cvt_pk_bf16_f32 v196, v182, v183
	v_cvt_pk_bf16_f32 v197, v184, v185
	ds_write_b64 v2, v[196:197] offset:9232
	v_pk_mul_f32 v[186:187], v[58:59], v[6:7] op_sel_hi:[1,0]
	v_pk_mul_f32 v[188:189], v[60:61], v[6:7] op_sel_hi:[1,0]
	v_cvt_pk_bf16_f32 v198, v186, v187
	v_cvt_pk_bf16_f32 v199, v188, v189
	ds_write_b64 v2, v[198:199] offset:9248
	v_pk_mul_f32 v[190:191], v[62:63], v[6:7] op_sel_hi:[1,0]
	v_pk_mul_f32 v[192:193], v[64:65], v[6:7] op_sel_hi:[1,0]
	v_cvt_pk_bf16_f32 v200, v190, v191
	v_cvt_pk_bf16_f32 v201, v192, v193
	ds_write_b64 v2, v[200:201] offset:9264
	v_pk_mul_f32 v[178:179], v[66:67], v[6:7] op_sel_hi:[1,0]
	v_pk_mul_f32 v[180:181], v[68:69], v[6:7] op_sel_hi:[1,0]
	v_cvt_pk_bf16_f32 v202, v178, v179
	v_cvt_pk_bf16_f32 v203, v180, v181
	ds_write_b64 v2, v[202:203] offset:9280
	v_pk_mul_f32 v[182:183], v[70:71], v[6:7] op_sel_hi:[1,0]
	v_pk_mul_f32 v[184:185], v[72:73], v[6:7] op_sel_hi:[1,0]
	v_cvt_pk_bf16_f32 v204, v182, v183
	v_cvt_pk_bf16_f32 v205, v184, v185
	ds_write_b64 v2, v[204:205] offset:9296
	v_pk_mul_f32 v[186:187], v[74:75], v[6:7] op_sel_hi:[1,0]
	v_pk_mul_f32 v[188:189], v[76:77], v[6:7] op_sel_hi:[1,0]
	v_cvt_pk_bf16_f32 v206, v186, v187
	v_cvt_pk_bf16_f32 v207, v188, v189
	ds_write_b64 v2, v[206:207] offset:9312
	v_pk_mul_f32 v[190:191], v[78:79], v[6:7] op_sel_hi:[1,0]
	v_pk_mul_f32 v[192:193], v[80:81], v[6:7] op_sel_hi:[1,0]
	v_cvt_pk_bf16_f32 v208, v190, v191
	v_cvt_pk_bf16_f32 v209, v192, v193
	ds_write_b64 v2, v[208:209] offset:9328
	s_waitcnt vmcnt(0)
; __device__ __forceinline__ unsigned pk2(float lo, float hi) { f32x2_t v = {lo, hi}; bf16x2_t b = __builtin_convertvector(v, bf16x2_t); return __builtin_bit_cast(unsigned, b); }
; __device__ __forceinline__ float fsigmoid(float x) { return __builtin_amdgcn_rcpf(1.f + fexp(-x)); }
;     ...
;       auto flush_rows = [&](u16* gbase, size_t ldd) {
; #pragma unroll
;         for (int it = 0; it < 16; ++it) {
;           const int r = it * 8 + (lane >> 3), ch = lane & 7;
;           *(u32x4*)(gbase + (size_t)r * ldd + ch * 8) = *(const u32x4*)(stg + r * LD + ch * 8);
;         }
;       };
;     ...
; #pragma unroll
;         for (int tt = 0; tt < 4; ++tt) {
;           u16* srow = stg + (tt * 32 + l31) * LD;
; #pragma unroll
;           for (int ct = 0; ct < 2; ++ct)
; #pragma unroll
;             for (int rq = 0; rq < 4; ++rq) {
;               float v[4];
; #pragma unroll
;               for (int e = 0; e < 4; ++e) { v[e] = acc[ct][tt][rq * 4 + e] * rsv[tt]; if (act) v[e] = v[e] * fsigmoid(v[e]); }
;               u32x2 w; w.x = pk2(v[0], v[1]); w.y = pk2(v[2], v[3]);
;               *(u32x2*)(srow + ct * 32 + 8 * rq + 4 * h) = w;
;             }
;         }
;         flush_rows(dst + (size_t)(m0 + wr * 128) * ldd + c0, (size_t)ldd);
	v_pk_mul_f32 v[178:179], v[18:19], v[4:5] op_sel_hi:[1,0]
	v_pk_mul_f32 v[180:181], v[20:21], v[4:5] op_sel_hi:[1,0]
	v_cvt_pk_bf16_f32 v194, v178, v179
	v_cvt_pk_bf16_f32 v195, v180, v181
	ds_write_b64 v2, v[194:195] offset:13824
	v_pk_mul_f32 v[182:183], v[22:23], v[4:5] op_sel_hi:[1,0]
	v_pk_mul_f32 v[184:185], v[24:25], v[4:5] op_sel_hi:[1,0]
	v_cvt_pk_bf16_f32 v196, v182, v183
	v_cvt_pk_bf16_f32 v197, v184, v185
	ds_write_b64 v2, v[196:197] offset:13840
	v_pk_mul_f32 v[186:187], v[26:27], v[4:5] op_sel_hi:[1,0]
	v_pk_mul_f32 v[188:189], v[28:29], v[4:5] op_sel_hi:[1,0]
	v_cvt_pk_bf16_f32 v198, v186, v187
	v_cvt_pk_bf16_f32 v199, v188, v189
	ds_write_b64 v2, v[198:199] offset:13856
	v_pk_mul_f32 v[190:191], v[30:31], v[4:5] op_sel_hi:[1,0]
	v_pk_mul_f32 v[192:193], v[32:33], v[4:5] op_sel_hi:[1,0]
	v_cvt_pk_bf16_f32 v200, v190, v191
	v_cvt_pk_bf16_f32 v201, v192, v193
	ds_write_b64 v2, v[200:201] offset:13872
	v_pk_mul_f32 v[178:179], v[34:35], v[4:5] op_sel_hi:[1,0]
	v_pk_mul_f32 v[180:181], v[36:37], v[4:5] op_sel_hi:[1,0]
	v_cvt_pk_bf16_f32 v202, v178, v179
	v_cvt_pk_bf16_f32 v203, v180, v181
	ds_write_b64 v2, v[202:203] offset:13888
	v_pk_mul_f32 v[182:183], v[38:39], v[4:5] op_sel_hi:[1,0]
	v_pk_mul_f32 v[184:185], v[40:41], v[4:5] op_sel_hi:[1,0]
	v_cvt_pk_bf16_f32 v204, v182, v183
	v_cvt_pk_bf16_f32 v205, v184, v185
	ds_write_b64 v2, v[204:205] offset:13904
	v_pk_mul_f32 v[186:187], v[42:43], v[4:5] op_sel_hi:[1,0]
	v_pk_mul_f32 v[188:189], v[44:45], v[4:5] op_sel_hi:[1,0]
	v_cvt_pk_bf16_f32 v206, v186, v187
	v_cvt_pk_bf16_f32 v207, v188, v189
	ds_write_b64 v2, v[206:207] offset:13920
	v_pk_mul_f32 v[190:191], v[46:47], v[4:5] op_sel_hi:[1,0]
	v_pk_mul_f32 v[192:193], v[48:49], v[4:5] op_sel_hi:[1,0]
	v_cvt_pk_bf16_f32 v208, v190, v191
	v_cvt_pk_bf16_f32 v209, v192, v193
	ds_write_b64 v2, v[208:209] offset:13936
	v_lshrrev_b32_e32 v7, 3, v147
	v_lshlrev_b32_e32 v9, 4, v225
	v_and_b32_e32 v9, 0x70, v9
	v_mul_u32_u24_e32 v11, 0x90, v7
	v_add3_u32 v11, s7, v11, v9
	v_mul_u32_u24_e32 v13, s34, v7
	v_lshl_add_u32 v13, v13, 1, v9
	s_mul_i32 s36, s34, s31
	s_add_i32 s36, s36, s20
	s_lshl_b32 s36, s36, 1
	s_lshl_b32 s31, s34, 4
	s_waitcnt lgkmcnt(0)
	s_add_u32 s36, s38, s36
	s_addc_u32 s37, s39, 0
	ds_read_b128 v[178:181], v11
	ds_read_b128 v[182:185], v11 offset:1152
	ds_read_b128 v[186:189], v11 offset:2304
	ds_read_b128 v[190:193], v11 offset:3456
	s_waitcnt lgkmcnt(3)
	global_store_dwordx4 v13, v[178:181], s[36:37] nt
	s_add_u32 s36, s36, s31
	s_addc_u32 s37, s37, 0
	ds_read_b128 v[178:181], v11 offset:4608
	s_waitcnt lgkmcnt(3)
	global_store_dwordx4 v13, v[182:185], s[36:37] nt
	s_add_u32 s36, s36, s31
	s_addc_u32 s37, s37, 0
	ds_read_b128 v[182:185], v11 offset:5760
	s_waitcnt lgkmcnt(3)
	global_store_dwordx4 v13, v[186:189], s[36:37] nt
	s_add_u32 s36, s36, s31
	s_addc_u32 s37, s37, 0
	ds_read_b128 v[186:189], v11 offset:6912
	s_waitcnt lgkmcnt(3)
	global_store_dwordx4 v13, v[190:193], s[36:37] nt
	s_add_u32 s36, s36, s31
	s_addc_u32 s37, s37, 0
	ds_read_b128 v[190:193], v11 offset:8064
	s_waitcnt lgkmcnt(3)
	global_store_dwordx4 v13, v[178:181], s[36:37] nt
	s_add_u32 s36, s36, s31
	s_addc_u32 s37, s37, 0
	ds_read_b128 v[178:181], v11 offset:9216
	s_waitcnt lgkmcnt(3)
	global_store_dwordx4 v13, v[182:185], s[36:37] nt
	s_add_u32 s36, s36, s31
	s_addc_u32 s37, s37, 0
	ds_read_b128 v[182:185], v11 offset:10368
	s_waitcnt lgkmcnt(3)
	global_store_dwordx4 v13, v[186:189], s[36:37] nt
	s_add_u32 s36, s36, s31
	s_addc_u32 s37, s37, 0
	ds_read_b128 v[186:189], v11 offset:11520
	s_waitcnt lgkmcnt(3)
	global_store_dwordx4 v13, v[190:193], s[36:37] nt
	s_add_u32 s36, s36, s31
	s_addc_u32 s37, s37, 0
	ds_read_b128 v[190:193], v11 offset:12672
	s_waitcnt lgkmcnt(3)
	global_store_dwordx4 v13, v[178:181], s[36:37] nt
	s_add_u32 s36, s36, s31
	s_addc_u32 s37, s37, 0
	ds_read_b128 v[178:181], v11 offset:13824
	s_waitcnt lgkmcnt(3)
	global_store_dwordx4 v13, v[182:185], s[36:37] nt
	s_add_u32 s36, s36, s31
	s_addc_u32 s37, s37, 0
	ds_read_b128 v[182:185], v11 offset:14976
	s_waitcnt lgkmcnt(3)
	global_store_dwordx4 v13, v[186:189], s[36:37] nt
	s_add_u32 s36, s36, s31
	s_addc_u32 s37, s37, 0
	ds_read_b128 v[186:189], v11 offset:16128
	s_waitcnt lgkmcnt(3)
	global_store_dwordx4 v13, v[190:193], s[36:37] nt
	s_add_u32 s36, s36, s31
	s_addc_u32 s37, s37, 0
	ds_read_b128 v[190:193], v11 offset:17280
	s_waitcnt lgkmcnt(3)
	global_store_dwordx4 v13, v[178:181], s[36:37] nt
	s_add_u32 s36, s36, s31
	s_addc_u32 s37, s37, 0
	s_waitcnt lgkmcnt(2)
	global_store_dwordx4 v13, v[182:185], s[36:37] nt
	s_add_u32 s36, s36, s31
	s_addc_u32 s37, s37, 0
	s_waitcnt lgkmcnt(1)
	global_store_dwordx4 v13, v[186:189], s[36:37] nt
	s_add_u32 s36, s36, s31
	s_addc_u32 s37, s37, 0
	s_waitcnt lgkmcnt(0)
	global_store_dwordx4 v13, v[190:193], s[36:37] nt
	s_add_u32 s36, s36, s31
	s_addc_u32 s37, s37, 0
	s_branch .LBB0_102
